# plus phase-8 prompt conv items hand-written: weights/LN constants resident, next window prefetched during LN+SiLU, exp/rcp SiLU
# speedup vs baseline: 1.0131x; 1.0085x over previous
.LBB0_1305:
	s_or_b64 exec, exec, s[66:67]
	s_cmpk_gt_i32 s2, 0x57f
	s_cbranch_scc1 .LBB0_1581
	v_lshlrev_b32_e32 v16, 3, v231
	v_lshlrev_b32_e32 v17, 4, v136
	s_mov_b64 s[6:7], s[22:23]
	global_load_dwordx2 v[140:141], v16, s[6:7]
	s_add_u32 s6, s6, 0x1000
	s_addc_u32 s7, s7, 0
	global_load_dwordx2 v[142:143], v16, s[6:7]
	s_add_u32 s6, s6, 0x1000
	s_addc_u32 s7, s7, 0
	global_load_dwordx2 v[144:145], v16, s[6:7]
	s_add_u32 s6, s6, 0x1000
	s_addc_u32 s7, s7, 0
	global_load_dwordx2 v[146:147], v16, s[6:7]
	s_add_u32 s6, s6, 0x1000
	s_addc_u32 s7, s7, 0
	global_load_dwordx2 v[148:149], v16, s[6:7]
	s_add_u32 s6, s6, 0x1000
	s_addc_u32 s7, s7, 0
	global_load_dwordx2 v[150:151], v16, s[6:7]
	s_add_u32 s6, s6, 0x1000
	s_addc_u32 s7, s7, 0
	global_load_dwordx2 v[152:153], v16, s[6:7]
	s_add_u32 s6, s6, 0x1000
	s_addc_u32 s7, s7, 0
	global_load_dwordx2 v[154:155], v16, s[6:7]
	s_add_u32 s6, s6, 0x1000
	s_addc_u32 s7, s7, 0
	global_load_dwordx2 v[156:157], v16, s[6:7]
	s_add_u32 s6, s6, 0x1000
	s_addc_u32 s7, s7, 0
	global_load_dwordx2 v[158:159], v16, s[6:7]
	s_add_u32 s6, s6, 0x1000
	s_addc_u32 s7, s7, 0
	global_load_dwordx2 v[160:161], v16, s[6:7]
	s_add_u32 s6, s6, 0x1000
	s_addc_u32 s7, s7, 0
	global_load_dwordx2 v[162:163], v16, s[6:7]
	s_add_u32 s6, s6, 0x1000
	s_addc_u32 s7, s7, 0
	global_load_dwordx2 v[164:165], v16, s[6:7]
	s_add_u32 s6, s6, 0x1000
	s_addc_u32 s7, s7, 0
	global_load_dwordx2 v[166:167], v16, s[6:7]
	s_add_u32 s6, s6, 0x1000
	s_addc_u32 s7, s7, 0
	global_load_dwordx2 v[168:169], v16, s[6:7]
	s_add_u32 s6, s6, 0x1000
	s_addc_u32 s7, s7, 0
	global_load_dwordx2 v[170:171], v16, s[6:7]
	s_add_u32 s6, s6, 0x1000
	s_addc_u32 s7, s7, 0
	global_load_dwordx2 v[172:173], v16, s[6:7]
	s_add_u32 s6, s6, 0x1000
	s_addc_u32 s7, s7, 0
	global_load_dwordx2 v[174:175], v16, s[6:7]
	s_add_u32 s6, s6, 0x1000
	s_addc_u32 s7, s7, 0
	global_load_dwordx2 v[176:177], v16, s[6:7]
	s_add_u32 s6, s6, 0x1000
	s_addc_u32 s7, s7, 0
	global_load_dwordx2 v[178:179], v16, s[6:7]
	s_add_u32 s6, s6, 0x1000
	s_addc_u32 s7, s7, 0
	global_load_dwordx2 v[180:181], v16, s[6:7]
	s_add_u32 s6, s6, 0x1000
	s_addc_u32 s7, s7, 0
	global_load_dwordx2 v[182:183], v16, s[6:7]
	s_add_u32 s6, s6, 0x1000
	s_addc_u32 s7, s7, 0
	global_load_dwordx2 v[184:185], v16, s[6:7]
	s_add_u32 s6, s6, 0x1000
	s_addc_u32 s7, s7, 0
	global_load_dwordx2 v[186:187], v16, s[6:7]
	s_add_u32 s6, s6, 0x1000
	s_addc_u32 s7, s7, 0
	global_load_dwordx2 v[188:189], v16, s[6:7]
	s_add_u32 s6, s6, 0x1000
	s_addc_u32 s7, s7, 0
	global_load_dwordx2 v[190:191], v16, s[6:7]
	s_add_u32 s6, s6, 0x1000
	s_addc_u32 s7, s7, 0
	global_load_dwordx2 v[192:193], v16, s[6:7]
	s_add_u32 s6, s6, 0x1000
	s_addc_u32 s7, s7, 0
	global_load_dwordx2 v[194:195], v16, s[6:7]
	s_add_u32 s6, s6, 0x1000
	s_addc_u32 s7, s7, 0
	global_load_dwordx2 v[196:197], v16, s[6:7]
	s_add_u32 s6, s6, 0x1000
	s_addc_u32 s7, s7, 0
	global_load_dwordx2 v[198:199], v16, s[6:7]
	s_add_u32 s6, s6, 0x1000
	s_addc_u32 s7, s7, 0
	global_load_dwordx2 v[200:201], v16, s[6:7]
	s_add_u32 s6, s6, 0x1000
	s_addc_u32 s7, s7, 0
	global_load_dwordx2 v[202:203], v16, s[24:25]
	global_load_dwordx4 v[204:207], v17, s[26:27] offset:0
	global_load_dwordx4 v[208:211], v17, s[26:27] offset:1024
	global_load_dwordx4 v[212:215], v17, s[26:27] offset:2048
	global_load_dwordx4 v[216:219], v17, s[26:27] offset:3072
	global_load_dwordx4 v[240:243], v17, s[36:37] offset:0
	global_load_dwordx4 v[244:247], v17, s[36:37] offset:1024
	global_load_dwordx4 v[248:251], v17, s[36:37] offset:2048
	global_load_dwordx4 v[124:127], v17, s[36:37] offset:3072
	global_load_dwordx4 v[128:131], v17, s[70:71] offset:0
	global_load_dwordx4 v[132:135], v17, s[70:71] offset:1024
	global_load_dwordx4 v[0:3], v17, s[70:71] offset:2048
	global_load_dwordx4 v[4:7], v17, s[70:71] offset:3072
	v_lshl_add_u32 v17, v230, 12, v17
	v_lshlrev_b32_e32 v19, 3, v136
	v_lshl_add_u32 v19, v230, 12, v19
	v_add_u32_e32 v19, 0x800, v19
	s_lshl_b32 s80, s2, 3
	s_sub_i32 s80, 30, s80
	s_lshl_b32 s3, s2, 15
	s_add_u32 s66, s42, 0x29700000
	s_addc_u32 s67, s43, 0
	s_add_u32 s66, s66, s3
	s_addc_u32 s67, s67, 0
	s_sub_u32 s66, s66, 0x1e000
	s_subb_u32 s67, s67, 0
	s_add_u32 s8, s42, 0x2bf00000
	s_addc_u32 s9, s43, 0
	s_add_u32 s8, s8, s3
	s_addc_u32 s9, s9, 0
	s_waitcnt vmcnt(0)
	s_mov_b64 s[6:7], s[66:67]
	s_cmp_gt_i32 s80, 0
	s_cbranch_scc1 .Lcv_z_1
	global_load_dwordx2 v[32:33], v16, s[6:7]
	s_branch .Lcv_n_2
.Lcv_z_1:
	v_mov_b32_e32 v32, 0
	v_mov_b32_e32 v33, 0
.Lcv_n_2:
	s_add_u32 s6, s6, 0x1000
	s_addc_u32 s7, s7, 0
	s_cmp_gt_i32 s80, 1
	s_cbranch_scc1 .Lcv_z_3
	global_load_dwordx2 v[34:35], v16, s[6:7]
	s_branch .Lcv_n_4
.Lcv_z_3:
	v_mov_b32_e32 v34, 0
	v_mov_b32_e32 v35, 0
.Lcv_n_4:
	s_add_u32 s6, s6, 0x1000
	s_addc_u32 s7, s7, 0
	s_cmp_gt_i32 s80, 2
	s_cbranch_scc1 .Lcv_z_5
	global_load_dwordx2 v[36:37], v16, s[6:7]
	s_branch .Lcv_n_6
.Lcv_z_5:
	v_mov_b32_e32 v36, 0
	v_mov_b32_e32 v37, 0
.Lcv_n_6:
	s_add_u32 s6, s6, 0x1000
	s_addc_u32 s7, s7, 0
	s_cmp_gt_i32 s80, 3
	s_cbranch_scc1 .Lcv_z_7
	global_load_dwordx2 v[38:39], v16, s[6:7]
	s_branch .Lcv_n_8
.Lcv_z_7:
	v_mov_b32_e32 v38, 0
	v_mov_b32_e32 v39, 0
.Lcv_n_8:
	s_add_u32 s6, s6, 0x1000
	s_addc_u32 s7, s7, 0
	s_cmp_gt_i32 s80, 4
	s_cbranch_scc1 .Lcv_z_9
	global_load_dwordx2 v[40:41], v16, s[6:7]
	s_branch .Lcv_n_10
.Lcv_z_9:
	v_mov_b32_e32 v40, 0
	v_mov_b32_e32 v41, 0
.Lcv_n_10:
	s_add_u32 s6, s6, 0x1000
	s_addc_u32 s7, s7, 0
	s_cmp_gt_i32 s80, 5
	s_cbranch_scc1 .Lcv_z_11
	global_load_dwordx2 v[42:43], v16, s[6:7]
	s_branch .Lcv_n_12
.Lcv_z_11:
	v_mov_b32_e32 v42, 0
	v_mov_b32_e32 v43, 0
.Lcv_n_12:
	s_add_u32 s6, s6, 0x1000
	s_addc_u32 s7, s7, 0
	s_cmp_gt_i32 s80, 6
	s_cbranch_scc1 .Lcv_z_13
	global_load_dwordx2 v[44:45], v16, s[6:7]
	s_branch .Lcv_n_14
.Lcv_z_13:
	v_mov_b32_e32 v44, 0
	v_mov_b32_e32 v45, 0
.Lcv_n_14:
	s_add_u32 s6, s6, 0x1000
	s_addc_u32 s7, s7, 0
	s_cmp_gt_i32 s80, 7
	s_cbranch_scc1 .Lcv_z_15
	global_load_dwordx2 v[46:47], v16, s[6:7]
	s_branch .Lcv_n_16
.Lcv_z_15:
	v_mov_b32_e32 v46, 0
	v_mov_b32_e32 v47, 0
.Lcv_n_16:
	s_add_u32 s6, s6, 0x1000
	s_addc_u32 s7, s7, 0
	s_cmp_gt_i32 s80, 8
	s_cbranch_scc1 .Lcv_z_17
	global_load_dwordx2 v[48:49], v16, s[6:7]
	s_branch .Lcv_n_18
.Lcv_z_17:
	v_mov_b32_e32 v48, 0
	v_mov_b32_e32 v49, 0
.Lcv_n_18:
	s_add_u32 s6, s6, 0x1000
	s_addc_u32 s7, s7, 0
	s_cmp_gt_i32 s80, 9
	s_cbranch_scc1 .Lcv_z_19
	global_load_dwordx2 v[50:51], v16, s[6:7]
	s_branch .Lcv_n_20
.Lcv_z_19:
	v_mov_b32_e32 v50, 0
	v_mov_b32_e32 v51, 0
.Lcv_n_20:
	s_add_u32 s6, s6, 0x1000
	s_addc_u32 s7, s7, 0
	s_cmp_gt_i32 s80, 10
	s_cbranch_scc1 .Lcv_z_21
	global_load_dwordx2 v[52:53], v16, s[6:7]
	s_branch .Lcv_n_22
.Lcv_z_21:
	v_mov_b32_e32 v52, 0
	v_mov_b32_e32 v53, 0
.Lcv_n_22:
	s_add_u32 s6, s6, 0x1000
	s_addc_u32 s7, s7, 0
	s_cmp_gt_i32 s80, 11
	s_cbranch_scc1 .Lcv_z_23
	global_load_dwordx2 v[54:55], v16, s[6:7]
	s_branch .Lcv_n_24
.Lcv_z_23:
	v_mov_b32_e32 v54, 0
	v_mov_b32_e32 v55, 0
.Lcv_n_24:
	s_add_u32 s6, s6, 0x1000
	s_addc_u32 s7, s7, 0
	s_cmp_gt_i32 s80, 12
	s_cbranch_scc1 .Lcv_z_25
	global_load_dwordx2 v[56:57], v16, s[6:7]
	s_branch .Lcv_n_26
.Lcv_z_25:
	v_mov_b32_e32 v56, 0
	v_mov_b32_e32 v57, 0
.Lcv_n_26:
	s_add_u32 s6, s6, 0x1000
	s_addc_u32 s7, s7, 0
	s_cmp_gt_i32 s80, 13
	s_cbranch_scc1 .Lcv_z_27
	global_load_dwordx2 v[58:59], v16, s[6:7]
	s_branch .Lcv_n_28
.Lcv_z_27:
	v_mov_b32_e32 v58, 0
	v_mov_b32_e32 v59, 0
.Lcv_n_28:
	s_add_u32 s6, s6, 0x1000
	s_addc_u32 s7, s7, 0
	s_cmp_gt_i32 s80, 14
	s_cbranch_scc1 .Lcv_z_29
	global_load_dwordx2 v[60:61], v16, s[6:7]
	s_branch .Lcv_n_30
.Lcv_z_29:
	v_mov_b32_e32 v60, 0
	v_mov_b32_e32 v61, 0
.Lcv_n_30:
	s_add_u32 s6, s6, 0x1000
	s_addc_u32 s7, s7, 0
	s_cmp_gt_i32 s80, 15
	s_cbranch_scc1 .Lcv_z_31
	global_load_dwordx2 v[62:63], v16, s[6:7]
	s_branch .Lcv_n_32
.Lcv_z_31:
	v_mov_b32_e32 v62, 0
	v_mov_b32_e32 v63, 0
.Lcv_n_32:
	s_add_u32 s6, s6, 0x1000
	s_addc_u32 s7, s7, 0
	s_cmp_gt_i32 s80, 16
	s_cbranch_scc1 .Lcv_z_33
	global_load_dwordx2 v[64:65], v16, s[6:7]
	s_branch .Lcv_n_34
.Lcv_z_33:
	v_mov_b32_e32 v64, 0
	v_mov_b32_e32 v65, 0
.Lcv_n_34:
	s_add_u32 s6, s6, 0x1000
	s_addc_u32 s7, s7, 0
	s_cmp_gt_i32 s80, 17
	s_cbranch_scc1 .Lcv_z_35
	global_load_dwordx2 v[66:67], v16, s[6:7]
	s_branch .Lcv_n_36
.Lcv_z_35:
	v_mov_b32_e32 v66, 0
	v_mov_b32_e32 v67, 0
.Lcv_n_36:
	s_add_u32 s6, s6, 0x1000
	s_addc_u32 s7, s7, 0
	s_cmp_gt_i32 s80, 18
	s_cbranch_scc1 .Lcv_z_37
	global_load_dwordx2 v[68:69], v16, s[6:7]
	s_branch .Lcv_n_38
.Lcv_z_37:
	v_mov_b32_e32 v68, 0
	v_mov_b32_e32 v69, 0
.Lcv_n_38:
	s_add_u32 s6, s6, 0x1000
	s_addc_u32 s7, s7, 0
	s_cmp_gt_i32 s80, 19
	s_cbranch_scc1 .Lcv_z_39
	global_load_dwordx2 v[70:71], v16, s[6:7]
	s_branch .Lcv_n_40
.Lcv_z_39:
	v_mov_b32_e32 v70, 0
	v_mov_b32_e32 v71, 0
.Lcv_n_40:
	s_add_u32 s6, s6, 0x1000
	s_addc_u32 s7, s7, 0
	s_cmp_gt_i32 s80, 20
	s_cbranch_scc1 .Lcv_z_41
	global_load_dwordx2 v[72:73], v16, s[6:7]
	s_branch .Lcv_n_42
.Lcv_z_41:
	v_mov_b32_e32 v72, 0
	v_mov_b32_e32 v73, 0
.Lcv_n_42:
	s_add_u32 s6, s6, 0x1000
	s_addc_u32 s7, s7, 0
	s_cmp_gt_i32 s80, 21
	s_cbranch_scc1 .Lcv_z_43
	global_load_dwordx2 v[74:75], v16, s[6:7]
	s_branch .Lcv_n_44
.Lcv_z_43:
	v_mov_b32_e32 v74, 0
	v_mov_b32_e32 v75, 0
.Lcv_n_44:
	s_add_u32 s6, s6, 0x1000
	s_addc_u32 s7, s7, 0
	s_cmp_gt_i32 s80, 22
	s_cbranch_scc1 .Lcv_z_45
	global_load_dwordx2 v[76:77], v16, s[6:7]
	s_branch .Lcv_n_46
.Lcv_z_45:
	v_mov_b32_e32 v76, 0
	v_mov_b32_e32 v77, 0
.Lcv_n_46:
	s_add_u32 s6, s6, 0x1000
	s_addc_u32 s7, s7, 0
	s_cmp_gt_i32 s80, 23
	s_cbranch_scc1 .Lcv_z_47
	global_load_dwordx2 v[78:79], v16, s[6:7]
	s_branch .Lcv_n_48
.Lcv_z_47:
	v_mov_b32_e32 v78, 0
	v_mov_b32_e32 v79, 0
.Lcv_n_48:
	s_add_u32 s6, s6, 0x1000
	s_addc_u32 s7, s7, 0
	s_cmp_gt_i32 s80, 24
	s_cbranch_scc1 .Lcv_z_49
	global_load_dwordx2 v[80:81], v16, s[6:7]
	s_branch .Lcv_n_50
.Lcv_z_49:
	v_mov_b32_e32 v80, 0
	v_mov_b32_e32 v81, 0
.Lcv_n_50:
	s_add_u32 s6, s6, 0x1000
	s_addc_u32 s7, s7, 0
	s_cmp_gt_i32 s80, 25
	s_cbranch_scc1 .Lcv_z_51
	global_load_dwordx2 v[82:83], v16, s[6:7]
	s_branch .Lcv_n_52
.Lcv_z_51:
	v_mov_b32_e32 v82, 0
	v_mov_b32_e32 v83, 0
.Lcv_n_52:
	s_add_u32 s6, s6, 0x1000
	s_addc_u32 s7, s7, 0
	s_cmp_gt_i32 s80, 26
	s_cbranch_scc1 .Lcv_z_53
	global_load_dwordx2 v[84:85], v16, s[6:7]
	s_branch .Lcv_n_54
.Lcv_z_53:
	v_mov_b32_e32 v84, 0
	v_mov_b32_e32 v85, 0
.Lcv_n_54:
	s_add_u32 s6, s6, 0x1000
	s_addc_u32 s7, s7, 0
	s_cmp_gt_i32 s80, 27
	s_cbranch_scc1 .Lcv_z_55
	global_load_dwordx2 v[86:87], v16, s[6:7]
	s_branch .Lcv_n_56
.Lcv_z_55:
	v_mov_b32_e32 v86, 0
	v_mov_b32_e32 v87, 0
.Lcv_n_56:
	s_add_u32 s6, s6, 0x1000
	s_addc_u32 s7, s7, 0
	s_cmp_gt_i32 s80, 28
	s_cbranch_scc1 .Lcv_z_57
	global_load_dwordx2 v[88:89], v16, s[6:7]
	s_branch .Lcv_n_58
.Lcv_z_57:
	v_mov_b32_e32 v88, 0
	v_mov_b32_e32 v89, 0
.Lcv_n_58:
	s_add_u32 s6, s6, 0x1000
	s_addc_u32 s7, s7, 0
	s_cmp_gt_i32 s80, 29
	s_cbranch_scc1 .Lcv_z_59
	global_load_dwordx2 v[90:91], v16, s[6:7]
	s_branch .Lcv_n_60
.Lcv_z_59:
	v_mov_b32_e32 v90, 0
	v_mov_b32_e32 v91, 0
.Lcv_n_60:
	s_add_u32 s6, s6, 0x1000
	s_addc_u32 s7, s7, 0
	global_load_dwordx2 v[92:93], v16, s[6:7]
	s_add_u32 s6, s6, 0x1000
	s_addc_u32 s7, s7, 0
	global_load_dwordx2 v[94:95], v16, s[6:7]
	s_add_u32 s6, s6, 0x1000
	s_addc_u32 s7, s7, 0
	global_load_dwordx2 v[96:97], v16, s[6:7]
	s_add_u32 s6, s6, 0x1000
	s_addc_u32 s7, s7, 0
	global_load_dwordx2 v[98:99], v16, s[6:7]
	s_add_u32 s6, s6, 0x1000
	s_addc_u32 s7, s7, 0
	global_load_dwordx2 v[100:101], v16, s[6:7]
	s_add_u32 s6, s6, 0x1000
	s_addc_u32 s7, s7, 0
	global_load_dwordx2 v[102:103], v16, s[6:7]
	s_add_u32 s6, s6, 0x1000
	s_addc_u32 s7, s7, 0
	global_load_dwordx2 v[104:105], v16, s[6:7]
	s_add_u32 s6, s6, 0x1000
	s_addc_u32 s7, s7, 0
	global_load_dwordx2 v[106:107], v16, s[6:7]
	s_add_u32 s6, s6, 0x1000
	s_addc_u32 s7, s7, 0
	s_add_u32 s66, s66, 0x800000
	s_addc_u32 s67, s67, 0
	v_mov_b32_e32 v108, v202
	v_mov_b32_e32 v109, v203
	v_mov_b32_e32 v110, v202
	v_mov_b32_e32 v111, v203
	v_mov_b32_e32 v112, v202
	v_mov_b32_e32 v113, v203
	v_mov_b32_e32 v114, v202
	v_mov_b32_e32 v115, v203
	v_mov_b32_e32 v116, v202
	v_mov_b32_e32 v117, v203
	v_mov_b32_e32 v118, v202
	v_mov_b32_e32 v119, v203
	v_mov_b32_e32 v120, v202
	v_mov_b32_e32 v121, v203
	v_mov_b32_e32 v122, v202
	v_mov_b32_e32 v123, v203
	s_waitcnt vmcnt(36)
	v_pk_fma_f32 v[108:109], v[140:141], v[32:33], v[108:109]
	v_pk_fma_f32 v[108:109], v[142:143], v[34:35], v[108:109]
	v_pk_fma_f32 v[110:111], v[140:141], v[34:35], v[110:111]
	s_waitcnt vmcnt(34)
	v_pk_fma_f32 v[108:109], v[144:145], v[36:37], v[108:109]
	v_pk_fma_f32 v[110:111], v[142:143], v[36:37], v[110:111]
	v_pk_fma_f32 v[112:113], v[140:141], v[36:37], v[112:113]
	v_pk_fma_f32 v[108:109], v[146:147], v[38:39], v[108:109]
	v_pk_fma_f32 v[110:111], v[144:145], v[38:39], v[110:111]
	v_pk_fma_f32 v[112:113], v[142:143], v[38:39], v[112:113]
	v_pk_fma_f32 v[114:115], v[140:141], v[38:39], v[114:115]
	s_waitcnt vmcnt(32)
	v_pk_fma_f32 v[108:109], v[148:149], v[40:41], v[108:109]
	v_pk_fma_f32 v[110:111], v[146:147], v[40:41], v[110:111]
	v_pk_fma_f32 v[112:113], v[144:145], v[40:41], v[112:113]
	v_pk_fma_f32 v[114:115], v[142:143], v[40:41], v[114:115]
	v_pk_fma_f32 v[116:117], v[140:141], v[40:41], v[116:117]
	v_pk_fma_f32 v[108:109], v[150:151], v[42:43], v[108:109]
	v_pk_fma_f32 v[110:111], v[148:149], v[42:43], v[110:111]
	v_pk_fma_f32 v[112:113], v[146:147], v[42:43], v[112:113]
	v_pk_fma_f32 v[114:115], v[144:145], v[42:43], v[114:115]
	v_pk_fma_f32 v[116:117], v[142:143], v[42:43], v[116:117]
	v_pk_fma_f32 v[118:119], v[140:141], v[42:43], v[118:119]
	s_waitcnt vmcnt(30)
	v_pk_fma_f32 v[108:109], v[152:153], v[44:45], v[108:109]
	v_pk_fma_f32 v[110:111], v[150:151], v[44:45], v[110:111]
	v_pk_fma_f32 v[112:113], v[148:149], v[44:45], v[112:113]
	v_pk_fma_f32 v[114:115], v[146:147], v[44:45], v[114:115]
	v_pk_fma_f32 v[116:117], v[144:145], v[44:45], v[116:117]
	v_pk_fma_f32 v[118:119], v[142:143], v[44:45], v[118:119]
	v_pk_fma_f32 v[120:121], v[140:141], v[44:45], v[120:121]
	v_pk_fma_f32 v[108:109], v[154:155], v[46:47], v[108:109]
	v_pk_fma_f32 v[110:111], v[152:153], v[46:47], v[110:111]
	v_pk_fma_f32 v[112:113], v[150:151], v[46:47], v[112:113]
	v_pk_fma_f32 v[114:115], v[148:149], v[46:47], v[114:115]
	v_pk_fma_f32 v[116:117], v[146:147], v[46:47], v[116:117]
	v_pk_fma_f32 v[118:119], v[144:145], v[46:47], v[118:119]
	v_pk_fma_f32 v[120:121], v[142:143], v[46:47], v[120:121]
	v_pk_fma_f32 v[122:123], v[140:141], v[46:47], v[122:123]
	s_waitcnt vmcnt(28)
	v_pk_fma_f32 v[108:109], v[156:157], v[48:49], v[108:109]
	v_pk_fma_f32 v[110:111], v[154:155], v[48:49], v[110:111]
	v_pk_fma_f32 v[112:113], v[152:153], v[48:49], v[112:113]
	v_pk_fma_f32 v[114:115], v[150:151], v[48:49], v[114:115]
	v_pk_fma_f32 v[116:117], v[148:149], v[48:49], v[116:117]
	v_pk_fma_f32 v[118:119], v[146:147], v[48:49], v[118:119]
	v_pk_fma_f32 v[120:121], v[144:145], v[48:49], v[120:121]
	v_pk_fma_f32 v[122:123], v[142:143], v[48:49], v[122:123]
	v_pk_fma_f32 v[108:109], v[158:159], v[50:51], v[108:109]
	v_pk_fma_f32 v[110:111], v[156:157], v[50:51], v[110:111]
	v_pk_fma_f32 v[112:113], v[154:155], v[50:51], v[112:113]
	v_pk_fma_f32 v[114:115], v[152:153], v[50:51], v[114:115]
	v_pk_fma_f32 v[116:117], v[150:151], v[50:51], v[116:117]
	v_pk_fma_f32 v[118:119], v[148:149], v[50:51], v[118:119]
	v_pk_fma_f32 v[120:121], v[146:147], v[50:51], v[120:121]
	v_pk_fma_f32 v[122:123], v[144:145], v[50:51], v[122:123]
	s_waitcnt vmcnt(26)
	v_pk_fma_f32 v[108:109], v[160:161], v[52:53], v[108:109]
	v_pk_fma_f32 v[110:111], v[158:159], v[52:53], v[110:111]
	v_pk_fma_f32 v[112:113], v[156:157], v[52:53], v[112:113]
	v_pk_fma_f32 v[114:115], v[154:155], v[52:53], v[114:115]
	v_pk_fma_f32 v[116:117], v[152:153], v[52:53], v[116:117]
	v_pk_fma_f32 v[118:119], v[150:151], v[52:53], v[118:119]
	v_pk_fma_f32 v[120:121], v[148:149], v[52:53], v[120:121]
	v_pk_fma_f32 v[122:123], v[146:147], v[52:53], v[122:123]
	v_pk_fma_f32 v[108:109], v[162:163], v[54:55], v[108:109]
	v_pk_fma_f32 v[110:111], v[160:161], v[54:55], v[110:111]
	v_pk_fma_f32 v[112:113], v[158:159], v[54:55], v[112:113]
	v_pk_fma_f32 v[114:115], v[156:157], v[54:55], v[114:115]
	v_pk_fma_f32 v[116:117], v[154:155], v[54:55], v[116:117]
	v_pk_fma_f32 v[118:119], v[152:153], v[54:55], v[118:119]
	v_pk_fma_f32 v[120:121], v[150:151], v[54:55], v[120:121]
	v_pk_fma_f32 v[122:123], v[148:149], v[54:55], v[122:123]
	s_waitcnt vmcnt(24)
	v_pk_fma_f32 v[108:109], v[164:165], v[56:57], v[108:109]
	v_pk_fma_f32 v[110:111], v[162:163], v[56:57], v[110:111]
	v_pk_fma_f32 v[112:113], v[160:161], v[56:57], v[112:113]
	v_pk_fma_f32 v[114:115], v[158:159], v[56:57], v[114:115]
	v_pk_fma_f32 v[116:117], v[156:157], v[56:57], v[116:117]
	v_pk_fma_f32 v[118:119], v[154:155], v[56:57], v[118:119]
	v_pk_fma_f32 v[120:121], v[152:153], v[56:57], v[120:121]
	v_pk_fma_f32 v[122:123], v[150:151], v[56:57], v[122:123]
	v_pk_fma_f32 v[108:109], v[166:167], v[58:59], v[108:109]
	v_pk_fma_f32 v[110:111], v[164:165], v[58:59], v[110:111]
	v_pk_fma_f32 v[112:113], v[162:163], v[58:59], v[112:113]
	v_pk_fma_f32 v[114:115], v[160:161], v[58:59], v[114:115]
	v_pk_fma_f32 v[116:117], v[158:159], v[58:59], v[116:117]
	v_pk_fma_f32 v[118:119], v[156:157], v[58:59], v[118:119]
	v_pk_fma_f32 v[120:121], v[154:155], v[58:59], v[120:121]
	v_pk_fma_f32 v[122:123], v[152:153], v[58:59], v[122:123]
	s_waitcnt vmcnt(22)
	v_pk_fma_f32 v[108:109], v[168:169], v[60:61], v[108:109]
	v_pk_fma_f32 v[110:111], v[166:167], v[60:61], v[110:111]
	v_pk_fma_f32 v[112:113], v[164:165], v[60:61], v[112:113]
	v_pk_fma_f32 v[114:115], v[162:163], v[60:61], v[114:115]
	v_pk_fma_f32 v[116:117], v[160:161], v[60:61], v[116:117]
	v_pk_fma_f32 v[118:119], v[158:159], v[60:61], v[118:119]
	v_pk_fma_f32 v[120:121], v[156:157], v[60:61], v[120:121]
	v_pk_fma_f32 v[122:123], v[154:155], v[60:61], v[122:123]
	v_pk_fma_f32 v[108:109], v[170:171], v[62:63], v[108:109]
	v_pk_fma_f32 v[110:111], v[168:169], v[62:63], v[110:111]
	v_pk_fma_f32 v[112:113], v[166:167], v[62:63], v[112:113]
	v_pk_fma_f32 v[114:115], v[164:165], v[62:63], v[114:115]
	v_pk_fma_f32 v[116:117], v[162:163], v[62:63], v[116:117]
	v_pk_fma_f32 v[118:119], v[160:161], v[62:63], v[118:119]
	v_pk_fma_f32 v[120:121], v[158:159], v[62:63], v[120:121]
	v_pk_fma_f32 v[122:123], v[156:157], v[62:63], v[122:123]
	s_waitcnt vmcnt(20)
	v_pk_fma_f32 v[108:109], v[172:173], v[64:65], v[108:109]
	v_pk_fma_f32 v[110:111], v[170:171], v[64:65], v[110:111]
	v_pk_fma_f32 v[112:113], v[168:169], v[64:65], v[112:113]
	v_pk_fma_f32 v[114:115], v[166:167], v[64:65], v[114:115]
	v_pk_fma_f32 v[116:117], v[164:165], v[64:65], v[116:117]
	v_pk_fma_f32 v[118:119], v[162:163], v[64:65], v[118:119]
	v_pk_fma_f32 v[120:121], v[160:161], v[64:65], v[120:121]
	v_pk_fma_f32 v[122:123], v[158:159], v[64:65], v[122:123]
	v_pk_fma_f32 v[108:109], v[174:175], v[66:67], v[108:109]
	v_pk_fma_f32 v[110:111], v[172:173], v[66:67], v[110:111]
	v_pk_fma_f32 v[112:113], v[170:171], v[66:67], v[112:113]
	v_pk_fma_f32 v[114:115], v[168:169], v[66:67], v[114:115]
	v_pk_fma_f32 v[116:117], v[166:167], v[66:67], v[116:117]
	v_pk_fma_f32 v[118:119], v[164:165], v[66:67], v[118:119]
	v_pk_fma_f32 v[120:121], v[162:163], v[66:67], v[120:121]
	v_pk_fma_f32 v[122:123], v[160:161], v[66:67], v[122:123]
	s_waitcnt vmcnt(18)
	v_pk_fma_f32 v[108:109], v[176:177], v[68:69], v[108:109]
	v_pk_fma_f32 v[110:111], v[174:175], v[68:69], v[110:111]
	v_pk_fma_f32 v[112:113], v[172:173], v[68:69], v[112:113]
	v_pk_fma_f32 v[114:115], v[170:171], v[68:69], v[114:115]
	v_pk_fma_f32 v[116:117], v[168:169], v[68:69], v[116:117]
	v_pk_fma_f32 v[118:119], v[166:167], v[68:69], v[118:119]
	v_pk_fma_f32 v[120:121], v[164:165], v[68:69], v[120:121]
	v_pk_fma_f32 v[122:123], v[162:163], v[68:69], v[122:123]
	v_pk_fma_f32 v[108:109], v[178:179], v[70:71], v[108:109]
	v_pk_fma_f32 v[110:111], v[176:177], v[70:71], v[110:111]
	v_pk_fma_f32 v[112:113], v[174:175], v[70:71], v[112:113]
	v_pk_fma_f32 v[114:115], v[172:173], v[70:71], v[114:115]
	v_pk_fma_f32 v[116:117], v[170:171], v[70:71], v[116:117]
	v_pk_fma_f32 v[118:119], v[168:169], v[70:71], v[118:119]
	v_pk_fma_f32 v[120:121], v[166:167], v[70:71], v[120:121]
	v_pk_fma_f32 v[122:123], v[164:165], v[70:71], v[122:123]
	s_waitcnt vmcnt(16)
	v_pk_fma_f32 v[108:109], v[180:181], v[72:73], v[108:109]
	v_pk_fma_f32 v[110:111], v[178:179], v[72:73], v[110:111]
	v_pk_fma_f32 v[112:113], v[176:177], v[72:73], v[112:113]
	v_pk_fma_f32 v[114:115], v[174:175], v[72:73], v[114:115]
	v_pk_fma_f32 v[116:117], v[172:173], v[72:73], v[116:117]
	v_pk_fma_f32 v[118:119], v[170:171], v[72:73], v[118:119]
	v_pk_fma_f32 v[120:121], v[168:169], v[72:73], v[120:121]
	v_pk_fma_f32 v[122:123], v[166:167], v[72:73], v[122:123]
	v_pk_fma_f32 v[108:109], v[182:183], v[74:75], v[108:109]
	v_pk_fma_f32 v[110:111], v[180:181], v[74:75], v[110:111]
	v_pk_fma_f32 v[112:113], v[178:179], v[74:75], v[112:113]
	v_pk_fma_f32 v[114:115], v[176:177], v[74:75], v[114:115]
	v_pk_fma_f32 v[116:117], v[174:175], v[74:75], v[116:117]
	v_pk_fma_f32 v[118:119], v[172:173], v[74:75], v[118:119]
	v_pk_fma_f32 v[120:121], v[170:171], v[74:75], v[120:121]
	v_pk_fma_f32 v[122:123], v[168:169], v[74:75], v[122:123]
	s_waitcnt vmcnt(14)
	v_pk_fma_f32 v[108:109], v[184:185], v[76:77], v[108:109]
	v_pk_fma_f32 v[110:111], v[182:183], v[76:77], v[110:111]
	v_pk_fma_f32 v[112:113], v[180:181], v[76:77], v[112:113]
	v_pk_fma_f32 v[114:115], v[178:179], v[76:77], v[114:115]
	v_pk_fma_f32 v[116:117], v[176:177], v[76:77], v[116:117]
	v_pk_fma_f32 v[118:119], v[174:175], v[76:77], v[118:119]
	v_pk_fma_f32 v[120:121], v[172:173], v[76:77], v[120:121]
	v_pk_fma_f32 v[122:123], v[170:171], v[76:77], v[122:123]
	v_pk_fma_f32 v[108:109], v[186:187], v[78:79], v[108:109]
	v_pk_fma_f32 v[110:111], v[184:185], v[78:79], v[110:111]
	v_pk_fma_f32 v[112:113], v[182:183], v[78:79], v[112:113]
	v_pk_fma_f32 v[114:115], v[180:181], v[78:79], v[114:115]
	v_pk_fma_f32 v[116:117], v[178:179], v[78:79], v[116:117]
	v_pk_fma_f32 v[118:119], v[176:177], v[78:79], v[118:119]
	v_pk_fma_f32 v[120:121], v[174:175], v[78:79], v[120:121]
	v_pk_fma_f32 v[122:123], v[172:173], v[78:79], v[122:123]
	s_waitcnt vmcnt(12)
	v_pk_fma_f32 v[108:109], v[188:189], v[80:81], v[108:109]
	v_pk_fma_f32 v[110:111], v[186:187], v[80:81], v[110:111]
	v_pk_fma_f32 v[112:113], v[184:185], v[80:81], v[112:113]
	v_pk_fma_f32 v[114:115], v[182:183], v[80:81], v[114:115]
	v_pk_fma_f32 v[116:117], v[180:181], v[80:81], v[116:117]
	v_pk_fma_f32 v[118:119], v[178:179], v[80:81], v[118:119]
	v_pk_fma_f32 v[120:121], v[176:177], v[80:81], v[120:121]
	v_pk_fma_f32 v[122:123], v[174:175], v[80:81], v[122:123]
	v_pk_fma_f32 v[108:109], v[190:191], v[82:83], v[108:109]
	v_pk_fma_f32 v[110:111], v[188:189], v[82:83], v[110:111]
	v_pk_fma_f32 v[112:113], v[186:187], v[82:83], v[112:113]
	v_pk_fma_f32 v[114:115], v[184:185], v[82:83], v[114:115]
	v_pk_fma_f32 v[116:117], v[182:183], v[82:83], v[116:117]
	v_pk_fma_f32 v[118:119], v[180:181], v[82:83], v[118:119]
	v_pk_fma_f32 v[120:121], v[178:179], v[82:83], v[120:121]
	v_pk_fma_f32 v[122:123], v[176:177], v[82:83], v[122:123]
	s_waitcnt vmcnt(10)
	v_pk_fma_f32 v[108:109], v[192:193], v[84:85], v[108:109]
	v_pk_fma_f32 v[110:111], v[190:191], v[84:85], v[110:111]
	v_pk_fma_f32 v[112:113], v[188:189], v[84:85], v[112:113]
	v_pk_fma_f32 v[114:115], v[186:187], v[84:85], v[114:115]
	v_pk_fma_f32 v[116:117], v[184:185], v[84:85], v[116:117]
	v_pk_fma_f32 v[118:119], v[182:183], v[84:85], v[118:119]
	v_pk_fma_f32 v[120:121], v[180:181], v[84:85], v[120:121]
	v_pk_fma_f32 v[122:123], v[178:179], v[84:85], v[122:123]
	v_pk_fma_f32 v[108:109], v[194:195], v[86:87], v[108:109]
	v_pk_fma_f32 v[110:111], v[192:193], v[86:87], v[110:111]
	v_pk_fma_f32 v[112:113], v[190:191], v[86:87], v[112:113]
	v_pk_fma_f32 v[114:115], v[188:189], v[86:87], v[114:115]
	v_pk_fma_f32 v[116:117], v[186:187], v[86:87], v[116:117]
	v_pk_fma_f32 v[118:119], v[184:185], v[86:87], v[118:119]
	v_pk_fma_f32 v[120:121], v[182:183], v[86:87], v[120:121]
	v_pk_fma_f32 v[122:123], v[180:181], v[86:87], v[122:123]
	s_waitcnt vmcnt(8)
	v_pk_fma_f32 v[108:109], v[196:197], v[88:89], v[108:109]
	v_pk_fma_f32 v[110:111], v[194:195], v[88:89], v[110:111]
	v_pk_fma_f32 v[112:113], v[192:193], v[88:89], v[112:113]
	v_pk_fma_f32 v[114:115], v[190:191], v[88:89], v[114:115]
	v_pk_fma_f32 v[116:117], v[188:189], v[88:89], v[116:117]
	v_pk_fma_f32 v[118:119], v[186:187], v[88:89], v[118:119]
	v_pk_fma_f32 v[120:121], v[184:185], v[88:89], v[120:121]
	v_pk_fma_f32 v[122:123], v[182:183], v[88:89], v[122:123]
	v_pk_fma_f32 v[108:109], v[198:199], v[90:91], v[108:109]
	v_pk_fma_f32 v[110:111], v[196:197], v[90:91], v[110:111]
	v_pk_fma_f32 v[112:113], v[194:195], v[90:91], v[112:113]
	v_pk_fma_f32 v[114:115], v[192:193], v[90:91], v[114:115]
	v_pk_fma_f32 v[116:117], v[190:191], v[90:91], v[116:117]
	v_pk_fma_f32 v[118:119], v[188:189], v[90:91], v[118:119]
	v_pk_fma_f32 v[120:121], v[186:187], v[90:91], v[120:121]
	v_pk_fma_f32 v[122:123], v[184:185], v[90:91], v[122:123]
	s_waitcnt vmcnt(6)
	v_pk_fma_f32 v[108:109], v[200:201], v[92:93], v[108:109]
	v_pk_fma_f32 v[110:111], v[198:199], v[92:93], v[110:111]
	v_pk_fma_f32 v[112:113], v[196:197], v[92:93], v[112:113]
	v_pk_fma_f32 v[114:115], v[194:195], v[92:93], v[114:115]
	v_pk_fma_f32 v[116:117], v[192:193], v[92:93], v[116:117]
	v_pk_fma_f32 v[118:119], v[190:191], v[92:93], v[118:119]
	v_pk_fma_f32 v[120:121], v[188:189], v[92:93], v[120:121]
	v_pk_fma_f32 v[122:123], v[186:187], v[92:93], v[122:123]
	v_pk_fma_f32 v[110:111], v[200:201], v[94:95], v[110:111]
	v_pk_fma_f32 v[112:113], v[198:199], v[94:95], v[112:113]
	v_pk_fma_f32 v[114:115], v[196:197], v[94:95], v[114:115]
	v_pk_fma_f32 v[116:117], v[194:195], v[94:95], v[116:117]
	v_pk_fma_f32 v[118:119], v[192:193], v[94:95], v[118:119]
	v_pk_fma_f32 v[120:121], v[190:191], v[94:95], v[120:121]
	v_pk_fma_f32 v[122:123], v[188:189], v[94:95], v[122:123]
	s_waitcnt vmcnt(4)
	v_pk_fma_f32 v[112:113], v[200:201], v[96:97], v[112:113]
	v_pk_fma_f32 v[114:115], v[198:199], v[96:97], v[114:115]
	v_pk_fma_f32 v[116:117], v[196:197], v[96:97], v[116:117]
	v_pk_fma_f32 v[118:119], v[194:195], v[96:97], v[118:119]
	v_pk_fma_f32 v[120:121], v[192:193], v[96:97], v[120:121]
	v_pk_fma_f32 v[122:123], v[190:191], v[96:97], v[122:123]
	v_pk_fma_f32 v[114:115], v[200:201], v[98:99], v[114:115]
	v_pk_fma_f32 v[116:117], v[198:199], v[98:99], v[116:117]
	v_pk_fma_f32 v[118:119], v[196:197], v[98:99], v[118:119]
	v_pk_fma_f32 v[120:121], v[194:195], v[98:99], v[120:121]
	v_pk_fma_f32 v[122:123], v[192:193], v[98:99], v[122:123]
	s_waitcnt vmcnt(2)
	v_pk_fma_f32 v[116:117], v[200:201], v[100:101], v[116:117]
	v_pk_fma_f32 v[118:119], v[198:199], v[100:101], v[118:119]
	v_pk_fma_f32 v[120:121], v[196:197], v[100:101], v[120:121]
	v_pk_fma_f32 v[122:123], v[194:195], v[100:101], v[122:123]
	v_pk_fma_f32 v[118:119], v[200:201], v[102:103], v[118:119]
	v_pk_fma_f32 v[120:121], v[198:199], v[102:103], v[120:121]
	v_pk_fma_f32 v[122:123], v[196:197], v[102:103], v[122:123]
	s_waitcnt vmcnt(0)
	v_pk_fma_f32 v[120:121], v[200:201], v[104:105], v[120:121]
	v_pk_fma_f32 v[122:123], v[198:199], v[104:105], v[122:123]
	v_pk_fma_f32 v[122:123], v[200:201], v[106:107], v[122:123]
	ds_write_b64 v16, v[108:109] offset:0
	ds_write_b64 v16, v[110:111] offset:4096
	ds_write_b64 v16, v[112:113] offset:8192
	ds_write_b64 v16, v[114:115] offset:12288
	ds_write_b64 v16, v[116:117] offset:16384
	ds_write_b64 v16, v[118:119] offset:20480
	ds_write_b64 v16, v[120:121] offset:24576
	ds_write_b64 v16, v[122:123] offset:28672
	s_waitcnt lgkmcnt(0)
	s_barrier
	s_mov_b64 s[6:7], s[66:67]
	s_cmp_gt_i32 s80, 0
	s_cbranch_scc1 .Lcv_z_61
	global_load_dwordx2 v[32:33], v16, s[6:7]
	s_branch .Lcv_n_62

.Lcv_n_120:
	s_add_u32 s6, s6, 0x1000
	s_addc_u32 s7, s7, 0
	global_load_dwordx2 v[92:93], v16, s[6:7]
	s_add_u32 s6, s6, 0x1000
	s_addc_u32 s7, s7, 0
	global_load_dwordx2 v[94:95], v16, s[6:7]
	s_add_u32 s6, s6, 0x1000
	s_addc_u32 s7, s7, 0
	global_load_dwordx2 v[96:97], v16, s[6:7]
	s_add_u32 s6, s6, 0x1000
	s_addc_u32 s7, s7, 0
	global_load_dwordx2 v[98:99], v16, s[6:7]
	s_add_u32 s6, s6, 0x1000
	s_addc_u32 s7, s7, 0
	global_load_dwordx2 v[100:101], v16, s[6:7]
	s_add_u32 s6, s6, 0x1000
	s_addc_u32 s7, s7, 0
	global_load_dwordx2 v[102:103], v16, s[6:7]
	s_add_u32 s6, s6, 0x1000
	s_addc_u32 s7, s7, 0
	global_load_dwordx2 v[104:105], v16, s[6:7]
	s_add_u32 s6, s6, 0x1000
	s_addc_u32 s7, s7, 0
	global_load_dwordx2 v[106:107], v16, s[6:7]
	s_add_u32 s6, s6, 0x1000
	s_addc_u32 s7, s7, 0
	s_add_u32 s66, s66, 0x800000
	s_addc_u32 s67, s67, 0
	ds_read_b128 v[8:11], v17 offset:0
	ds_read_b128 v[12:15], v17 offset:1024
	ds_read_b128 v[20:23], v17 offset:2048
	ds_read_b128 v[24:27], v17 offset:3072
	s_waitcnt lgkmcnt(0)
	s_barrier
	v_pk_add_f32 v[108:109], v[8:9], v[10:11]
	v_pk_add_f32 v[108:109], v[108:109], v[12:13]
	v_pk_add_f32 v[108:109], v[108:109], v[14:15]
	v_pk_add_f32 v[108:109], v[108:109], v[20:21]
	v_pk_add_f32 v[108:109], v[108:109], v[22:23]
	v_pk_add_f32 v[108:109], v[108:109], v[24:25]
	v_pk_add_f32 v[108:109], v[108:109], v[26:27]
	v_add_f32_e32 v108, v108, v109
	s_nop 1
	v_add_f32_dpp v108, v108, v108 quad_perm:[1,0,3,2] row_mask:0xf bank_mask:0xf bound_ctrl:1
	s_nop 1
	v_add_f32_dpp v108, v108, v108 quad_perm:[2,3,0,1] row_mask:0xf bank_mask:0xf bound_ctrl:1
	s_nop 1
	v_add_f32_dpp v108, v108, v108 row_half_mirror row_mask:0xf bank_mask:0xf bound_ctrl:1
	s_nop 1
	v_add_f32_dpp v108, v108, v108 row_mirror row_mask:0xf bank_mask:0xf bound_ctrl:1
	v_mov_b32_e32 v114, v108
	s_nop 1
	v_permlane16_swap_b32 v108, v114
	s_nop 0
	v_add_f32_e32 v108, v108, v114
	v_mov_b32_e32 v114, v108
	s_nop 1
	v_permlane32_swap_b32 v108, v114
	s_nop 0
	v_add_f32_e32 v108, v108, v114
	v_mul_f32_e32 v110, 0x3a800000, v108
	v_pk_add_f32 v[8:9], v[8:9], v[110:111] op_sel_hi:[1,0] neg_lo:[0,1] neg_hi:[0,1]
	v_pk_add_f32 v[10:11], v[10:11], v[110:111] op_sel_hi:[1,0] neg_lo:[0,1] neg_hi:[0,1]
	v_pk_add_f32 v[12:13], v[12:13], v[110:111] op_sel_hi:[1,0] neg_lo:[0,1] neg_hi:[0,1]
	v_pk_add_f32 v[14:15], v[14:15], v[110:111] op_sel_hi:[1,0] neg_lo:[0,1] neg_hi:[0,1]
	v_pk_add_f32 v[20:21], v[20:21], v[110:111] op_sel_hi:[1,0] neg_lo:[0,1] neg_hi:[0,1]
	v_pk_add_f32 v[22:23], v[22:23], v[110:111] op_sel_hi:[1,0] neg_lo:[0,1] neg_hi:[0,1]
	v_pk_add_f32 v[24:25], v[24:25], v[110:111] op_sel_hi:[1,0] neg_lo:[0,1] neg_hi:[0,1]
	v_pk_add_f32 v[26:27], v[26:27], v[110:111] op_sel_hi:[1,0] neg_lo:[0,1] neg_hi:[0,1]
	v_pk_mul_f32 v[108:109], v[8:9], v[8:9]
	v_pk_fma_f32 v[108:109], v[10:11], v[10:11], v[108:109]
	v_pk_fma_f32 v[108:109], v[12:13], v[12:13], v[108:109]
	v_pk_fma_f32 v[108:109], v[14:15], v[14:15], v[108:109]
	v_pk_fma_f32 v[108:109], v[20:21], v[20:21], v[108:109]
	v_pk_fma_f32 v[108:109], v[22:23], v[22:23], v[108:109]
	v_pk_fma_f32 v[108:109], v[24:25], v[24:25], v[108:109]
	v_pk_fma_f32 v[108:109], v[26:27], v[26:27], v[108:109]
	v_add_f32_e32 v108, v108, v109
	s_nop 1
	v_add_f32_dpp v108, v108, v108 quad_perm:[1,0,3,2] row_mask:0xf bank_mask:0xf bound_ctrl:1
	s_nop 1
	v_add_f32_dpp v108, v108, v108 quad_perm:[2,3,0,1] row_mask:0xf bank_mask:0xf bound_ctrl:1
	s_nop 1
	v_add_f32_dpp v108, v108, v108 row_half_mirror row_mask:0xf bank_mask:0xf bound_ctrl:1
	s_nop 1
	v_add_f32_dpp v108, v108, v108 row_mirror row_mask:0xf bank_mask:0xf bound_ctrl:1
	v_mov_b32_e32 v114, v108
	s_nop 1
	v_permlane16_swap_b32 v108, v114
	s_nop 0
	v_add_f32_e32 v108, v108, v114
	v_mov_b32_e32 v114, v108
	s_nop 1
	v_permlane32_swap_b32 v108, v114
	s_nop 0
	v_add_f32_e32 v108, v108, v114
	v_mul_f32_e32 v112, 0x3a800000, v108
	v_add_f32_e32 v112, 0x3727c5ac, v112
	v_rsq_f32_e32 v112, v112
	s_nop 0
	v_pk_mul_f32 v[116:117], v[204:205], v[112:113] op_sel_hi:[1,0]
	v_pk_fma_f32 v[8:9], v[8:9], v[116:117], v[240:241]
	v_pk_mul_f32 v[116:117], v[206:207], v[112:113] op_sel_hi:[1,0]
	v_pk_fma_f32 v[10:11], v[10:11], v[116:117], v[242:243]
	v_pk_mul_f32 v[116:117], v[208:209], v[112:113] op_sel_hi:[1,0]
	v_pk_fma_f32 v[12:13], v[12:13], v[116:117], v[244:245]
	v_pk_mul_f32 v[116:117], v[210:211], v[112:113] op_sel_hi:[1,0]
	v_pk_fma_f32 v[14:15], v[14:15], v[116:117], v[246:247]
	v_pk_mul_f32 v[116:117], v[212:213], v[112:113] op_sel_hi:[1,0]
	v_pk_fma_f32 v[20:21], v[20:21], v[116:117], v[248:249]
	v_pk_mul_f32 v[116:117], v[214:215], v[112:113] op_sel_hi:[1,0]
	v_pk_fma_f32 v[22:23], v[22:23], v[116:117], v[250:251]
	v_pk_mul_f32 v[116:117], v[216:217], v[112:113] op_sel_hi:[1,0]
	v_pk_fma_f32 v[24:25], v[24:25], v[116:117], v[124:125]
	v_pk_mul_f32 v[116:117], v[218:219], v[112:113] op_sel_hi:[1,0]
	v_pk_fma_f32 v[26:27], v[26:27], v[116:117], v[126:127]
	v_mul_f32_e32 v118, 0xbfb8aa3b, v8
	v_mul_f32_e32 v119, 0xbfb8aa3b, v9
	v_mul_f32_e32 v120, 0xbfb8aa3b, v10
	v_mul_f32_e32 v121, 0xbfb8aa3b, v11
	v_mul_f32_e32 v122, 0xbfb8aa3b, v12
	v_mul_f32_e32 v123, 0xbfb8aa3b, v13
	v_mul_f32_e32 v108, 0xbfb8aa3b, v14
	v_mul_f32_e32 v109, 0xbfb8aa3b, v15
	v_mul_f32_e32 v110, 0xbfb8aa3b, v20
	v_mul_f32_e32 v111, 0xbfb8aa3b, v21
	v_mul_f32_e32 v112, 0xbfb8aa3b, v22
	v_mul_f32_e32 v113, 0xbfb8aa3b, v23
	v_mul_f32_e32 v114, 0xbfb8aa3b, v24
	v_mul_f32_e32 v115, 0xbfb8aa3b, v25
	v_mul_f32_e32 v116, 0xbfb8aa3b, v26
	v_mul_f32_e32 v117, 0xbfb8aa3b, v27
	v_exp_f32_e32 v118, v118
	v_exp_f32_e32 v119, v119
	v_exp_f32_e32 v120, v120
	v_exp_f32_e32 v121, v121
	v_exp_f32_e32 v122, v122
	v_exp_f32_e32 v123, v123
	v_exp_f32_e32 v108, v108
	v_exp_f32_e32 v109, v109
	v_exp_f32_e32 v110, v110
	v_exp_f32_e32 v111, v111
	v_exp_f32_e32 v112, v112
	v_exp_f32_e32 v113, v113
	v_exp_f32_e32 v114, v114
	v_exp_f32_e32 v115, v115
	v_exp_f32_e32 v116, v116
	v_exp_f32_e32 v117, v117
	v_add_f32_e32 v118, 1.0, v118
	v_add_f32_e32 v119, 1.0, v119
	v_add_f32_e32 v120, 1.0, v120
	v_add_f32_e32 v121, 1.0, v121
	v_add_f32_e32 v122, 1.0, v122
	v_add_f32_e32 v123, 1.0, v123
	v_add_f32_e32 v108, 1.0, v108
	v_add_f32_e32 v109, 1.0, v109
	v_add_f32_e32 v110, 1.0, v110
	v_add_f32_e32 v111, 1.0, v111
	v_add_f32_e32 v112, 1.0, v112
	v_add_f32_e32 v113, 1.0, v113
	v_add_f32_e32 v114, 1.0, v114
	v_add_f32_e32 v115, 1.0, v115
	v_add_f32_e32 v116, 1.0, v116
	v_add_f32_e32 v117, 1.0, v117
	v_rcp_f32_e32 v118, v118
	v_rcp_f32_e32 v119, v119
	v_rcp_f32_e32 v120, v120
	v_rcp_f32_e32 v121, v121
	v_rcp_f32_e32 v122, v122
	v_rcp_f32_e32 v123, v123
	v_rcp_f32_e32 v108, v108
	v_rcp_f32_e32 v109, v109
	v_rcp_f32_e32 v110, v110
	v_rcp_f32_e32 v111, v111
	v_rcp_f32_e32 v112, v112
	v_rcp_f32_e32 v113, v113
	v_rcp_f32_e32 v114, v114
	v_rcp_f32_e32 v115, v115
	v_rcp_f32_e32 v116, v116
	v_rcp_f32_e32 v117, v117
	v_mul_f32_e32 v8, v8, v118
	v_mul_f32_e32 v9, v9, v119
	v_mul_f32_e32 v10, v10, v120
	v_mul_f32_e32 v11, v11, v121
	v_mul_f32_e32 v12, v12, v122
	v_mul_f32_e32 v13, v13, v123
	v_mul_f32_e32 v14, v14, v108
	v_mul_f32_e32 v15, v15, v109
	v_mul_f32_e32 v20, v20, v110
	v_mul_f32_e32 v21, v21, v111
	v_mul_f32_e32 v22, v22, v112
	v_mul_f32_e32 v23, v23, v113
	v_mul_f32_e32 v24, v24, v114
	v_mul_f32_e32 v25, v25, v115
	v_mul_f32_e32 v26, v26, v116
	v_mul_f32_e32 v27, v27, v117
	v_pk_mul_f32 v[8:9], v[8:9], v[128:129]
	v_pk_mul_f32 v[10:11], v[10:11], v[130:131]
	v_pk_mul_f32 v[12:13], v[12:13], v[132:133]
	v_pk_mul_f32 v[14:15], v[14:15], v[134:135]
	v_pk_mul_f32 v[20:21], v[20:21], v[0:1]
	v_pk_mul_f32 v[22:23], v[22:23], v[2:3]
	v_pk_mul_f32 v[24:25], v[24:25], v[4:5]
	v_pk_mul_f32 v[26:27], v[26:27], v[6:7]
	v_cvt_pk_bf16_f32 v8, v8, v9
	v_cvt_pk_bf16_f32 v9, v10, v11
	v_cvt_pk_bf16_f32 v12, v12, v13
	v_cvt_pk_bf16_f32 v13, v14, v15
	v_cvt_pk_bf16_f32 v20, v20, v21
	v_cvt_pk_bf16_f32 v21, v22, v23
	v_cvt_pk_bf16_f32 v24, v24, v25
	v_cvt_pk_bf16_f32 v25, v26, v27
	global_store_dwordx2 v19, v[8:9], s[8:9] offset:0
	global_store_dwordx2 v19, v[12:13], s[8:9] offset:512
	global_store_dwordx2 v19, v[20:21], s[8:9] offset:1024
	global_store_dwordx2 v19, v[24:25], s[8:9] offset:1536
	s_add_u32 s8, s8, 0x800000
	s_addc_u32 s9, s9, 0
	v_mov_b32_e32 v108, v202
	v_mov_b32_e32 v109, v203
	v_mov_b32_e32 v110, v202
	v_mov_b32_e32 v111, v203
	v_mov_b32_e32 v112, v202
	v_mov_b32_e32 v113, v203
	v_mov_b32_e32 v114, v202
	v_mov_b32_e32 v115, v203
	v_mov_b32_e32 v116, v202
	v_mov_b32_e32 v117, v203
	v_mov_b32_e32 v118, v202
	v_mov_b32_e32 v119, v203
	v_mov_b32_e32 v120, v202
	v_mov_b32_e32 v121, v203
	v_mov_b32_e32 v122, v202
	v_mov_b32_e32 v123, v203
	s_waitcnt vmcnt(40)
	v_pk_fma_f32 v[108:109], v[140:141], v[32:33], v[108:109]
	v_pk_fma_f32 v[108:109], v[142:143], v[34:35], v[108:109]
	v_pk_fma_f32 v[110:111], v[140:141], v[34:35], v[110:111]
	s_waitcnt vmcnt(38)
	v_pk_fma_f32 v[108:109], v[144:145], v[36:37], v[108:109]
	v_pk_fma_f32 v[110:111], v[142:143], v[36:37], v[110:111]
	v_pk_fma_f32 v[112:113], v[140:141], v[36:37], v[112:113]
	v_pk_fma_f32 v[108:109], v[146:147], v[38:39], v[108:109]
	v_pk_fma_f32 v[110:111], v[144:145], v[38:39], v[110:111]
	v_pk_fma_f32 v[112:113], v[142:143], v[38:39], v[112:113]
	v_pk_fma_f32 v[114:115], v[140:141], v[38:39], v[114:115]
	s_waitcnt vmcnt(36)
	v_pk_fma_f32 v[108:109], v[148:149], v[40:41], v[108:109]
	v_pk_fma_f32 v[110:111], v[146:147], v[40:41], v[110:111]
	v_pk_fma_f32 v[112:113], v[144:145], v[40:41], v[112:113]
	v_pk_fma_f32 v[114:115], v[142:143], v[40:41], v[114:115]
	v_pk_fma_f32 v[116:117], v[140:141], v[40:41], v[116:117]
	v_pk_fma_f32 v[108:109], v[150:151], v[42:43], v[108:109]
	v_pk_fma_f32 v[110:111], v[148:149], v[42:43], v[110:111]
	v_pk_fma_f32 v[112:113], v[146:147], v[42:43], v[112:113]
	v_pk_fma_f32 v[114:115], v[144:145], v[42:43], v[114:115]
	v_pk_fma_f32 v[116:117], v[142:143], v[42:43], v[116:117]
	v_pk_fma_f32 v[118:119], v[140:141], v[42:43], v[118:119]
	s_waitcnt vmcnt(34)
	v_pk_fma_f32 v[108:109], v[152:153], v[44:45], v[108:109]
	v_pk_fma_f32 v[110:111], v[150:151], v[44:45], v[110:111]
	v_pk_fma_f32 v[112:113], v[148:149], v[44:45], v[112:113]
	v_pk_fma_f32 v[114:115], v[146:147], v[44:45], v[114:115]
	v_pk_fma_f32 v[116:117], v[144:145], v[44:45], v[116:117]
	v_pk_fma_f32 v[118:119], v[142:143], v[44:45], v[118:119]
	v_pk_fma_f32 v[120:121], v[140:141], v[44:45], v[120:121]
	v_pk_fma_f32 v[108:109], v[154:155], v[46:47], v[108:109]
	v_pk_fma_f32 v[110:111], v[152:153], v[46:47], v[110:111]
	v_pk_fma_f32 v[112:113], v[150:151], v[46:47], v[112:113]
	v_pk_fma_f32 v[114:115], v[148:149], v[46:47], v[114:115]
	v_pk_fma_f32 v[116:117], v[146:147], v[46:47], v[116:117]
	v_pk_fma_f32 v[118:119], v[144:145], v[46:47], v[118:119]
	v_pk_fma_f32 v[120:121], v[142:143], v[46:47], v[120:121]
	v_pk_fma_f32 v[122:123], v[140:141], v[46:47], v[122:123]
	s_waitcnt vmcnt(32)
	v_pk_fma_f32 v[108:109], v[156:157], v[48:49], v[108:109]
	v_pk_fma_f32 v[110:111], v[154:155], v[48:49], v[110:111]
	v_pk_fma_f32 v[112:113], v[152:153], v[48:49], v[112:113]
	v_pk_fma_f32 v[114:115], v[150:151], v[48:49], v[114:115]
	v_pk_fma_f32 v[116:117], v[148:149], v[48:49], v[116:117]
	v_pk_fma_f32 v[118:119], v[146:147], v[48:49], v[118:119]
	v_pk_fma_f32 v[120:121], v[144:145], v[48:49], v[120:121]
	v_pk_fma_f32 v[122:123], v[142:143], v[48:49], v[122:123]
	v_pk_fma_f32 v[108:109], v[158:159], v[50:51], v[108:109]
	v_pk_fma_f32 v[110:111], v[156:157], v[50:51], v[110:111]
	v_pk_fma_f32 v[112:113], v[154:155], v[50:51], v[112:113]
	v_pk_fma_f32 v[114:115], v[152:153], v[50:51], v[114:115]
	v_pk_fma_f32 v[116:117], v[150:151], v[50:51], v[116:117]
	v_pk_fma_f32 v[118:119], v[148:149], v[50:51], v[118:119]
	v_pk_fma_f32 v[120:121], v[146:147], v[50:51], v[120:121]
	v_pk_fma_f32 v[122:123], v[144:145], v[50:51], v[122:123]
	s_waitcnt vmcnt(30)
	v_pk_fma_f32 v[108:109], v[160:161], v[52:53], v[108:109]
	v_pk_fma_f32 v[110:111], v[158:159], v[52:53], v[110:111]
	v_pk_fma_f32 v[112:113], v[156:157], v[52:53], v[112:113]
	v_pk_fma_f32 v[114:115], v[154:155], v[52:53], v[114:115]
	v_pk_fma_f32 v[116:117], v[152:153], v[52:53], v[116:117]
	v_pk_fma_f32 v[118:119], v[150:151], v[52:53], v[118:119]
	v_pk_fma_f32 v[120:121], v[148:149], v[52:53], v[120:121]
	v_pk_fma_f32 v[122:123], v[146:147], v[52:53], v[122:123]
	v_pk_fma_f32 v[108:109], v[162:163], v[54:55], v[108:109]
	v_pk_fma_f32 v[110:111], v[160:161], v[54:55], v[110:111]
	v_pk_fma_f32 v[112:113], v[158:159], v[54:55], v[112:113]
	v_pk_fma_f32 v[114:115], v[156:157], v[54:55], v[114:115]
	v_pk_fma_f32 v[116:117], v[154:155], v[54:55], v[116:117]
	v_pk_fma_f32 v[118:119], v[152:153], v[54:55], v[118:119]
	v_pk_fma_f32 v[120:121], v[150:151], v[54:55], v[120:121]
	v_pk_fma_f32 v[122:123], v[148:149], v[54:55], v[122:123]
	s_waitcnt vmcnt(28)
	v_pk_fma_f32 v[108:109], v[164:165], v[56:57], v[108:109]
	v_pk_fma_f32 v[110:111], v[162:163], v[56:57], v[110:111]
	v_pk_fma_f32 v[112:113], v[160:161], v[56:57], v[112:113]
	v_pk_fma_f32 v[114:115], v[158:159], v[56:57], v[114:115]
	v_pk_fma_f32 v[116:117], v[156:157], v[56:57], v[116:117]
	v_pk_fma_f32 v[118:119], v[154:155], v[56:57], v[118:119]
	v_pk_fma_f32 v[120:121], v[152:153], v[56:57], v[120:121]
	v_pk_fma_f32 v[122:123], v[150:151], v[56:57], v[122:123]
	v_pk_fma_f32 v[108:109], v[166:167], v[58:59], v[108:109]
	v_pk_fma_f32 v[110:111], v[164:165], v[58:59], v[110:111]
	v_pk_fma_f32 v[112:113], v[162:163], v[58:59], v[112:113]
	v_pk_fma_f32 v[114:115], v[160:161], v[58:59], v[114:115]
	v_pk_fma_f32 v[116:117], v[158:159], v[58:59], v[116:117]
	v_pk_fma_f32 v[118:119], v[156:157], v[58:59], v[118:119]
	v_pk_fma_f32 v[120:121], v[154:155], v[58:59], v[120:121]
	v_pk_fma_f32 v[122:123], v[152:153], v[58:59], v[122:123]
	s_waitcnt vmcnt(26)
	v_pk_fma_f32 v[108:109], v[168:169], v[60:61], v[108:109]
	v_pk_fma_f32 v[110:111], v[166:167], v[60:61], v[110:111]
	v_pk_fma_f32 v[112:113], v[164:165], v[60:61], v[112:113]
	v_pk_fma_f32 v[114:115], v[162:163], v[60:61], v[114:115]
	v_pk_fma_f32 v[116:117], v[160:161], v[60:61], v[116:117]
	v_pk_fma_f32 v[118:119], v[158:159], v[60:61], v[118:119]
	v_pk_fma_f32 v[120:121], v[156:157], v[60:61], v[120:121]
	v_pk_fma_f32 v[122:123], v[154:155], v[60:61], v[122:123]
	v_pk_fma_f32 v[108:109], v[170:171], v[62:63], v[108:109]
	v_pk_fma_f32 v[110:111], v[168:169], v[62:63], v[110:111]
	v_pk_fma_f32 v[112:113], v[166:167], v[62:63], v[112:113]
	v_pk_fma_f32 v[114:115], v[164:165], v[62:63], v[114:115]
	v_pk_fma_f32 v[116:117], v[162:163], v[62:63], v[116:117]
	v_pk_fma_f32 v[118:119], v[160:161], v[62:63], v[118:119]
	v_pk_fma_f32 v[120:121], v[158:159], v[62:63], v[120:121]
	v_pk_fma_f32 v[122:123], v[156:157], v[62:63], v[122:123]
	s_waitcnt vmcnt(24)
	v_pk_fma_f32 v[108:109], v[172:173], v[64:65], v[108:109]
	v_pk_fma_f32 v[110:111], v[170:171], v[64:65], v[110:111]
	v_pk_fma_f32 v[112:113], v[168:169], v[64:65], v[112:113]
	v_pk_fma_f32 v[114:115], v[166:167], v[64:65], v[114:115]
	v_pk_fma_f32 v[116:117], v[164:165], v[64:65], v[116:117]
	v_pk_fma_f32 v[118:119], v[162:163], v[64:65], v[118:119]
	v_pk_fma_f32 v[120:121], v[160:161], v[64:65], v[120:121]
	v_pk_fma_f32 v[122:123], v[158:159], v[64:65], v[122:123]
	v_pk_fma_f32 v[108:109], v[174:175], v[66:67], v[108:109]
	v_pk_fma_f32 v[110:111], v[172:173], v[66:67], v[110:111]
	v_pk_fma_f32 v[112:113], v[170:171], v[66:67], v[112:113]
	v_pk_fma_f32 v[114:115], v[168:169], v[66:67], v[114:115]
	v_pk_fma_f32 v[116:117], v[166:167], v[66:67], v[116:117]
	v_pk_fma_f32 v[118:119], v[164:165], v[66:67], v[118:119]
	v_pk_fma_f32 v[120:121], v[162:163], v[66:67], v[120:121]
	v_pk_fma_f32 v[122:123], v[160:161], v[66:67], v[122:123]
	s_waitcnt vmcnt(22)
	v_pk_fma_f32 v[108:109], v[176:177], v[68:69], v[108:109]
	v_pk_fma_f32 v[110:111], v[174:175], v[68:69], v[110:111]
	v_pk_fma_f32 v[112:113], v[172:173], v[68:69], v[112:113]
	v_pk_fma_f32 v[114:115], v[170:171], v[68:69], v[114:115]
	v_pk_fma_f32 v[116:117], v[168:169], v[68:69], v[116:117]
	v_pk_fma_f32 v[118:119], v[166:167], v[68:69], v[118:119]
	v_pk_fma_f32 v[120:121], v[164:165], v[68:69], v[120:121]
	v_pk_fma_f32 v[122:123], v[162:163], v[68:69], v[122:123]
	v_pk_fma_f32 v[108:109], v[178:179], v[70:71], v[108:109]
	v_pk_fma_f32 v[110:111], v[176:177], v[70:71], v[110:111]
	v_pk_fma_f32 v[112:113], v[174:175], v[70:71], v[112:113]
	v_pk_fma_f32 v[114:115], v[172:173], v[70:71], v[114:115]
	v_pk_fma_f32 v[116:117], v[170:171], v[70:71], v[116:117]
	v_pk_fma_f32 v[118:119], v[168:169], v[70:71], v[118:119]
	v_pk_fma_f32 v[120:121], v[166:167], v[70:71], v[120:121]
	v_pk_fma_f32 v[122:123], v[164:165], v[70:71], v[122:123]
	s_waitcnt vmcnt(20)
	v_pk_fma_f32 v[108:109], v[180:181], v[72:73], v[108:109]
	v_pk_fma_f32 v[110:111], v[178:179], v[72:73], v[110:111]
	v_pk_fma_f32 v[112:113], v[176:177], v[72:73], v[112:113]
	v_pk_fma_f32 v[114:115], v[174:175], v[72:73], v[114:115]
	v_pk_fma_f32 v[116:117], v[172:173], v[72:73], v[116:117]
	v_pk_fma_f32 v[118:119], v[170:171], v[72:73], v[118:119]
	v_pk_fma_f32 v[120:121], v[168:169], v[72:73], v[120:121]
	v_pk_fma_f32 v[122:123], v[166:167], v[72:73], v[122:123]
	v_pk_fma_f32 v[108:109], v[182:183], v[74:75], v[108:109]
	v_pk_fma_f32 v[110:111], v[180:181], v[74:75], v[110:111]
	v_pk_fma_f32 v[112:113], v[178:179], v[74:75], v[112:113]
	v_pk_fma_f32 v[114:115], v[176:177], v[74:75], v[114:115]
	v_pk_fma_f32 v[116:117], v[174:175], v[74:75], v[116:117]
	v_pk_fma_f32 v[118:119], v[172:173], v[74:75], v[118:119]
	v_pk_fma_f32 v[120:121], v[170:171], v[74:75], v[120:121]
	v_pk_fma_f32 v[122:123], v[168:169], v[74:75], v[122:123]
	s_waitcnt vmcnt(18)
	v_pk_fma_f32 v[108:109], v[184:185], v[76:77], v[108:109]
	v_pk_fma_f32 v[110:111], v[182:183], v[76:77], v[110:111]
	v_pk_fma_f32 v[112:113], v[180:181], v[76:77], v[112:113]
	v_pk_fma_f32 v[114:115], v[178:179], v[76:77], v[114:115]
	v_pk_fma_f32 v[116:117], v[176:177], v[76:77], v[116:117]
	v_pk_fma_f32 v[118:119], v[174:175], v[76:77], v[118:119]
	v_pk_fma_f32 v[120:121], v[172:173], v[76:77], v[120:121]
	v_pk_fma_f32 v[122:123], v[170:171], v[76:77], v[122:123]
	v_pk_fma_f32 v[108:109], v[186:187], v[78:79], v[108:109]
	v_pk_fma_f32 v[110:111], v[184:185], v[78:79], v[110:111]
	v_pk_fma_f32 v[112:113], v[182:183], v[78:79], v[112:113]
	v_pk_fma_f32 v[114:115], v[180:181], v[78:79], v[114:115]
	v_pk_fma_f32 v[116:117], v[178:179], v[78:79], v[116:117]
	v_pk_fma_f32 v[118:119], v[176:177], v[78:79], v[118:119]
	v_pk_fma_f32 v[120:121], v[174:175], v[78:79], v[120:121]
	v_pk_fma_f32 v[122:123], v[172:173], v[78:79], v[122:123]
	s_waitcnt vmcnt(16)
	v_pk_fma_f32 v[108:109], v[188:189], v[80:81], v[108:109]
	v_pk_fma_f32 v[110:111], v[186:187], v[80:81], v[110:111]
	v_pk_fma_f32 v[112:113], v[184:185], v[80:81], v[112:113]
	v_pk_fma_f32 v[114:115], v[182:183], v[80:81], v[114:115]
	v_pk_fma_f32 v[116:117], v[180:181], v[80:81], v[116:117]
	v_pk_fma_f32 v[118:119], v[178:179], v[80:81], v[118:119]
	v_pk_fma_f32 v[120:121], v[176:177], v[80:81], v[120:121]
	v_pk_fma_f32 v[122:123], v[174:175], v[80:81], v[122:123]
	v_pk_fma_f32 v[108:109], v[190:191], v[82:83], v[108:109]
	v_pk_fma_f32 v[110:111], v[188:189], v[82:83], v[110:111]
	v_pk_fma_f32 v[112:113], v[186:187], v[82:83], v[112:113]
	v_pk_fma_f32 v[114:115], v[184:185], v[82:83], v[114:115]
	v_pk_fma_f32 v[116:117], v[182:183], v[82:83], v[116:117]
	v_pk_fma_f32 v[118:119], v[180:181], v[82:83], v[118:119]
	v_pk_fma_f32 v[120:121], v[178:179], v[82:83], v[120:121]
	v_pk_fma_f32 v[122:123], v[176:177], v[82:83], v[122:123]
	s_waitcnt vmcnt(14)
	v_pk_fma_f32 v[108:109], v[192:193], v[84:85], v[108:109]
	v_pk_fma_f32 v[110:111], v[190:191], v[84:85], v[110:111]
	v_pk_fma_f32 v[112:113], v[188:189], v[84:85], v[112:113]
	v_pk_fma_f32 v[114:115], v[186:187], v[84:85], v[114:115]
	v_pk_fma_f32 v[116:117], v[184:185], v[84:85], v[116:117]
	v_pk_fma_f32 v[118:119], v[182:183], v[84:85], v[118:119]
	v_pk_fma_f32 v[120:121], v[180:181], v[84:85], v[120:121]
	v_pk_fma_f32 v[122:123], v[178:179], v[84:85], v[122:123]
	v_pk_fma_f32 v[108:109], v[194:195], v[86:87], v[108:109]
	v_pk_fma_f32 v[110:111], v[192:193], v[86:87], v[110:111]
	v_pk_fma_f32 v[112:113], v[190:191], v[86:87], v[112:113]
	v_pk_fma_f32 v[114:115], v[188:189], v[86:87], v[114:115]
	v_pk_fma_f32 v[116:117], v[186:187], v[86:87], v[116:117]
	v_pk_fma_f32 v[118:119], v[184:185], v[86:87], v[118:119]
	v_pk_fma_f32 v[120:121], v[182:183], v[86:87], v[120:121]
	v_pk_fma_f32 v[122:123], v[180:181], v[86:87], v[122:123]
	s_waitcnt vmcnt(12)
	v_pk_fma_f32 v[108:109], v[196:197], v[88:89], v[108:109]
	v_pk_fma_f32 v[110:111], v[194:195], v[88:89], v[110:111]
	v_pk_fma_f32 v[112:113], v[192:193], v[88:89], v[112:113]
	v_pk_fma_f32 v[114:115], v[190:191], v[88:89], v[114:115]
	v_pk_fma_f32 v[116:117], v[188:189], v[88:89], v[116:117]
	v_pk_fma_f32 v[118:119], v[186:187], v[88:89], v[118:119]
	v_pk_fma_f32 v[120:121], v[184:185], v[88:89], v[120:121]
	v_pk_fma_f32 v[122:123], v[182:183], v[88:89], v[122:123]
	v_pk_fma_f32 v[108:109], v[198:199], v[90:91], v[108:109]
	v_pk_fma_f32 v[110:111], v[196:197], v[90:91], v[110:111]
	v_pk_fma_f32 v[112:113], v[194:195], v[90:91], v[112:113]
	v_pk_fma_f32 v[114:115], v[192:193], v[90:91], v[114:115]
	v_pk_fma_f32 v[116:117], v[190:191], v[90:91], v[116:117]
	v_pk_fma_f32 v[118:119], v[188:189], v[90:91], v[118:119]
	v_pk_fma_f32 v[120:121], v[186:187], v[90:91], v[120:121]
	v_pk_fma_f32 v[122:123], v[184:185], v[90:91], v[122:123]
	s_waitcnt vmcnt(10)
	v_pk_fma_f32 v[108:109], v[200:201], v[92:93], v[108:109]
	v_pk_fma_f32 v[110:111], v[198:199], v[92:93], v[110:111]
	v_pk_fma_f32 v[112:113], v[196:197], v[92:93], v[112:113]
	v_pk_fma_f32 v[114:115], v[194:195], v[92:93], v[114:115]
	v_pk_fma_f32 v[116:117], v[192:193], v[92:93], v[116:117]
	v_pk_fma_f32 v[118:119], v[190:191], v[92:93], v[118:119]
	v_pk_fma_f32 v[120:121], v[188:189], v[92:93], v[120:121]
	v_pk_fma_f32 v[122:123], v[186:187], v[92:93], v[122:123]
	v_pk_fma_f32 v[110:111], v[200:201], v[94:95], v[110:111]
	v_pk_fma_f32 v[112:113], v[198:199], v[94:95], v[112:113]
	v_pk_fma_f32 v[114:115], v[196:197], v[94:95], v[114:115]
	v_pk_fma_f32 v[116:117], v[194:195], v[94:95], v[116:117]
	v_pk_fma_f32 v[118:119], v[192:193], v[94:95], v[118:119]
	v_pk_fma_f32 v[120:121], v[190:191], v[94:95], v[120:121]
	v_pk_fma_f32 v[122:123], v[188:189], v[94:95], v[122:123]
	s_waitcnt vmcnt(8)
	v_pk_fma_f32 v[112:113], v[200:201], v[96:97], v[112:113]
	v_pk_fma_f32 v[114:115], v[198:199], v[96:97], v[114:115]
	v_pk_fma_f32 v[116:117], v[196:197], v[96:97], v[116:117]
	v_pk_fma_f32 v[118:119], v[194:195], v[96:97], v[118:119]
	v_pk_fma_f32 v[120:121], v[192:193], v[96:97], v[120:121]
	v_pk_fma_f32 v[122:123], v[190:191], v[96:97], v[122:123]
	v_pk_fma_f32 v[114:115], v[200:201], v[98:99], v[114:115]
	v_pk_fma_f32 v[116:117], v[198:199], v[98:99], v[116:117]
	v_pk_fma_f32 v[118:119], v[196:197], v[98:99], v[118:119]
	v_pk_fma_f32 v[120:121], v[194:195], v[98:99], v[120:121]
	v_pk_fma_f32 v[122:123], v[192:193], v[98:99], v[122:123]
	s_waitcnt vmcnt(6)
	v_pk_fma_f32 v[116:117], v[200:201], v[100:101], v[116:117]
	v_pk_fma_f32 v[118:119], v[198:199], v[100:101], v[118:119]
	v_pk_fma_f32 v[120:121], v[196:197], v[100:101], v[120:121]
	v_pk_fma_f32 v[122:123], v[194:195], v[100:101], v[122:123]
	v_pk_fma_f32 v[118:119], v[200:201], v[102:103], v[118:119]
	v_pk_fma_f32 v[120:121], v[198:199], v[102:103], v[120:121]
	v_pk_fma_f32 v[122:123], v[196:197], v[102:103], v[122:123]
	s_waitcnt vmcnt(4)
	v_pk_fma_f32 v[120:121], v[200:201], v[104:105], v[120:121]
	v_pk_fma_f32 v[122:123], v[198:199], v[104:105], v[122:123]
	v_pk_fma_f32 v[122:123], v[200:201], v[106:107], v[122:123]
	ds_write_b64 v16, v[108:109] offset:0
	ds_write_b64 v16, v[110:111] offset:4096
	ds_write_b64 v16, v[112:113] offset:8192
	ds_write_b64 v16, v[114:115] offset:12288
	ds_write_b64 v16, v[116:117] offset:16384
	ds_write_b64 v16, v[118:119] offset:20480
	ds_write_b64 v16, v[120:121] offset:24576
	ds_write_b64 v16, v[122:123] offset:28672
	s_waitcnt lgkmcnt(0)
	s_barrier
	s_mov_b64 s[6:7], s[66:67]
	s_cmp_gt_i32 s80, 0
	s_cbranch_scc1 .Lcv_z_121
	global_load_dwordx2 v[32:33], v16, s[6:7]
	s_branch .Lcv_n_122

.Lcv_n_240:
	s_add_u32 s6, s6, 0x1000
	s_addc_u32 s7, s7, 0
	global_load_dwordx2 v[92:93], v16, s[6:7]
	s_add_u32 s6, s6, 0x1000
	s_addc_u32 s7, s7, 0
	global_load_dwordx2 v[94:95], v16, s[6:7]
	s_add_u32 s6, s6, 0x1000
	s_addc_u32 s7, s7, 0
	global_load_dwordx2 v[96:97], v16, s[6:7]
	s_add_u32 s6, s6, 0x1000
	s_addc_u32 s7, s7, 0
	global_load_dwordx2 v[98:99], v16, s[6:7]
	s_add_u32 s6, s6, 0x1000
	s_addc_u32 s7, s7, 0
	global_load_dwordx2 v[100:101], v16, s[6:7]
	s_add_u32 s6, s6, 0x1000
	s_addc_u32 s7, s7, 0
	global_load_dwordx2 v[102:103], v16, s[6:7]
	s_add_u32 s6, s6, 0x1000
	s_addc_u32 s7, s7, 0
	global_load_dwordx2 v[104:105], v16, s[6:7]
	s_add_u32 s6, s6, 0x1000
	s_addc_u32 s7, s7, 0
	global_load_dwordx2 v[106:107], v16, s[6:7]
	s_add_u32 s6, s6, 0x1000
	s_addc_u32 s7, s7, 0
	s_add_u32 s66, s66, 0x800000
	s_addc_u32 s67, s67, 0
	ds_read_b128 v[8:11], v17 offset:0
	ds_read_b128 v[12:15], v17 offset:1024
	ds_read_b128 v[20:23], v17 offset:2048
	ds_read_b128 v[24:27], v17 offset:3072
	s_waitcnt lgkmcnt(0)
	s_barrier
	v_pk_add_f32 v[108:109], v[8:9], v[10:11]
	v_pk_add_f32 v[108:109], v[108:109], v[12:13]
	v_pk_add_f32 v[108:109], v[108:109], v[14:15]
	v_pk_add_f32 v[108:109], v[108:109], v[20:21]
	v_pk_add_f32 v[108:109], v[108:109], v[22:23]
	v_pk_add_f32 v[108:109], v[108:109], v[24:25]
	v_pk_add_f32 v[108:109], v[108:109], v[26:27]
	v_add_f32_e32 v108, v108, v109
	s_nop 1
	v_add_f32_dpp v108, v108, v108 quad_perm:[1,0,3,2] row_mask:0xf bank_mask:0xf bound_ctrl:1
	s_nop 1
	v_add_f32_dpp v108, v108, v108 quad_perm:[2,3,0,1] row_mask:0xf bank_mask:0xf bound_ctrl:1
	s_nop 1
	v_add_f32_dpp v108, v108, v108 row_half_mirror row_mask:0xf bank_mask:0xf bound_ctrl:1
	s_nop 1
	v_add_f32_dpp v108, v108, v108 row_mirror row_mask:0xf bank_mask:0xf bound_ctrl:1
	v_mov_b32_e32 v114, v108
	s_nop 1
	v_permlane16_swap_b32 v108, v114
	s_nop 0
	v_add_f32_e32 v108, v108, v114
	v_mov_b32_e32 v114, v108
	s_nop 1
	v_permlane32_swap_b32 v108, v114
	s_nop 0
	v_add_f32_e32 v108, v108, v114
	v_mul_f32_e32 v110, 0x3a800000, v108
	v_pk_add_f32 v[8:9], v[8:9], v[110:111] op_sel_hi:[1,0] neg_lo:[0,1] neg_hi:[0,1]
	v_pk_add_f32 v[10:11], v[10:11], v[110:111] op_sel_hi:[1,0] neg_lo:[0,1] neg_hi:[0,1]
	v_pk_add_f32 v[12:13], v[12:13], v[110:111] op_sel_hi:[1,0] neg_lo:[0,1] neg_hi:[0,1]
	v_pk_add_f32 v[14:15], v[14:15], v[110:111] op_sel_hi:[1,0] neg_lo:[0,1] neg_hi:[0,1]
	v_pk_add_f32 v[20:21], v[20:21], v[110:111] op_sel_hi:[1,0] neg_lo:[0,1] neg_hi:[0,1]
	v_pk_add_f32 v[22:23], v[22:23], v[110:111] op_sel_hi:[1,0] neg_lo:[0,1] neg_hi:[0,1]
	v_pk_add_f32 v[24:25], v[24:25], v[110:111] op_sel_hi:[1,0] neg_lo:[0,1] neg_hi:[0,1]
	v_pk_add_f32 v[26:27], v[26:27], v[110:111] op_sel_hi:[1,0] neg_lo:[0,1] neg_hi:[0,1]
	v_pk_mul_f32 v[108:109], v[8:9], v[8:9]
	v_pk_fma_f32 v[108:109], v[10:11], v[10:11], v[108:109]
	v_pk_fma_f32 v[108:109], v[12:13], v[12:13], v[108:109]
	v_pk_fma_f32 v[108:109], v[14:15], v[14:15], v[108:109]
	v_pk_fma_f32 v[108:109], v[20:21], v[20:21], v[108:109]
	v_pk_fma_f32 v[108:109], v[22:23], v[22:23], v[108:109]
	v_pk_fma_f32 v[108:109], v[24:25], v[24:25], v[108:109]
	v_pk_fma_f32 v[108:109], v[26:27], v[26:27], v[108:109]
	v_add_f32_e32 v108, v108, v109
	s_nop 1
	v_add_f32_dpp v108, v108, v108 quad_perm:[1,0,3,2] row_mask:0xf bank_mask:0xf bound_ctrl:1
	s_nop 1
	v_add_f32_dpp v108, v108, v108 quad_perm:[2,3,0,1] row_mask:0xf bank_mask:0xf bound_ctrl:1
	s_nop 1
	v_add_f32_dpp v108, v108, v108 row_half_mirror row_mask:0xf bank_mask:0xf bound_ctrl:1
	s_nop 1
	v_add_f32_dpp v108, v108, v108 row_mirror row_mask:0xf bank_mask:0xf bound_ctrl:1
	v_mov_b32_e32 v114, v108
	s_nop 1
	v_permlane16_swap_b32 v108, v114
	s_nop 0
	v_add_f32_e32 v108, v108, v114
	v_mov_b32_e32 v114, v108
	s_nop 1
	v_permlane32_swap_b32 v108, v114
	s_nop 0
	v_add_f32_e32 v108, v108, v114
	v_mul_f32_e32 v112, 0x3a800000, v108
	v_add_f32_e32 v112, 0x3727c5ac, v112
	v_rsq_f32_e32 v112, v112
	s_nop 0
	v_pk_mul_f32 v[116:117], v[204:205], v[112:113] op_sel_hi:[1,0]
	v_pk_fma_f32 v[8:9], v[8:9], v[116:117], v[240:241]
	v_pk_mul_f32 v[116:117], v[206:207], v[112:113] op_sel_hi:[1,0]
	v_pk_fma_f32 v[10:11], v[10:11], v[116:117], v[242:243]
	v_pk_mul_f32 v[116:117], v[208:209], v[112:113] op_sel_hi:[1,0]
	v_pk_fma_f32 v[12:13], v[12:13], v[116:117], v[244:245]
	v_pk_mul_f32 v[116:117], v[210:211], v[112:113] op_sel_hi:[1,0]
	v_pk_fma_f32 v[14:15], v[14:15], v[116:117], v[246:247]
	v_pk_mul_f32 v[116:117], v[212:213], v[112:113] op_sel_hi:[1,0]
	v_pk_fma_f32 v[20:21], v[20:21], v[116:117], v[248:249]
	v_pk_mul_f32 v[116:117], v[214:215], v[112:113] op_sel_hi:[1,0]
	v_pk_fma_f32 v[22:23], v[22:23], v[116:117], v[250:251]
	v_pk_mul_f32 v[116:117], v[216:217], v[112:113] op_sel_hi:[1,0]
	v_pk_fma_f32 v[24:25], v[24:25], v[116:117], v[124:125]
	v_pk_mul_f32 v[116:117], v[218:219], v[112:113] op_sel_hi:[1,0]
	v_pk_fma_f32 v[26:27], v[26:27], v[116:117], v[126:127]
	v_mul_f32_e32 v118, 0xbfb8aa3b, v8
	v_mul_f32_e32 v119, 0xbfb8aa3b, v9
	v_mul_f32_e32 v120, 0xbfb8aa3b, v10
	v_mul_f32_e32 v121, 0xbfb8aa3b, v11
	v_mul_f32_e32 v122, 0xbfb8aa3b, v12
	v_mul_f32_e32 v123, 0xbfb8aa3b, v13
	v_mul_f32_e32 v108, 0xbfb8aa3b, v14
	v_mul_f32_e32 v109, 0xbfb8aa3b, v15
	v_mul_f32_e32 v110, 0xbfb8aa3b, v20
	v_mul_f32_e32 v111, 0xbfb8aa3b, v21
	v_mul_f32_e32 v112, 0xbfb8aa3b, v22
	v_mul_f32_e32 v113, 0xbfb8aa3b, v23
	v_mul_f32_e32 v114, 0xbfb8aa3b, v24
	v_mul_f32_e32 v115, 0xbfb8aa3b, v25
	v_mul_f32_e32 v116, 0xbfb8aa3b, v26
	v_mul_f32_e32 v117, 0xbfb8aa3b, v27
	v_exp_f32_e32 v118, v118
	v_exp_f32_e32 v119, v119
	v_exp_f32_e32 v120, v120
	v_exp_f32_e32 v121, v121
	v_exp_f32_e32 v122, v122
	v_exp_f32_e32 v123, v123
	v_exp_f32_e32 v108, v108
	v_exp_f32_e32 v109, v109
	v_exp_f32_e32 v110, v110
	v_exp_f32_e32 v111, v111
	v_exp_f32_e32 v112, v112
	v_exp_f32_e32 v113, v113
	v_exp_f32_e32 v114, v114
	v_exp_f32_e32 v115, v115
	v_exp_f32_e32 v116, v116
	v_exp_f32_e32 v117, v117
	v_add_f32_e32 v118, 1.0, v118
	v_add_f32_e32 v119, 1.0, v119
	v_add_f32_e32 v120, 1.0, v120
	v_add_f32_e32 v121, 1.0, v121
	v_add_f32_e32 v122, 1.0, v122
	v_add_f32_e32 v123, 1.0, v123
	v_add_f32_e32 v108, 1.0, v108
	v_add_f32_e32 v109, 1.0, v109
	v_add_f32_e32 v110, 1.0, v110
	v_add_f32_e32 v111, 1.0, v111
	v_add_f32_e32 v112, 1.0, v112
	v_add_f32_e32 v113, 1.0, v113
	v_add_f32_e32 v114, 1.0, v114
	v_add_f32_e32 v115, 1.0, v115
	v_add_f32_e32 v116, 1.0, v116
	v_add_f32_e32 v117, 1.0, v117
	v_rcp_f32_e32 v118, v118
	v_rcp_f32_e32 v119, v119
	v_rcp_f32_e32 v120, v120
	v_rcp_f32_e32 v121, v121
	v_rcp_f32_e32 v122, v122
	v_rcp_f32_e32 v123, v123
	v_rcp_f32_e32 v108, v108
	v_rcp_f32_e32 v109, v109
	v_rcp_f32_e32 v110, v110
	v_rcp_f32_e32 v111, v111
	v_rcp_f32_e32 v112, v112
	v_rcp_f32_e32 v113, v113
	v_rcp_f32_e32 v114, v114
	v_rcp_f32_e32 v115, v115
	v_rcp_f32_e32 v116, v116
	v_rcp_f32_e32 v117, v117
	v_mul_f32_e32 v8, v8, v118
	v_mul_f32_e32 v9, v9, v119
	v_mul_f32_e32 v10, v10, v120
	v_mul_f32_e32 v11, v11, v121
	v_mul_f32_e32 v12, v12, v122
	v_mul_f32_e32 v13, v13, v123
	v_mul_f32_e32 v14, v14, v108
	v_mul_f32_e32 v15, v15, v109
	v_mul_f32_e32 v20, v20, v110
	v_mul_f32_e32 v21, v21, v111
	v_mul_f32_e32 v22, v22, v112
	v_mul_f32_e32 v23, v23, v113
	v_mul_f32_e32 v24, v24, v114
	v_mul_f32_e32 v25, v25, v115
	v_mul_f32_e32 v26, v26, v116
	v_mul_f32_e32 v27, v27, v117
	v_pk_mul_f32 v[8:9], v[8:9], v[128:129]
	v_pk_mul_f32 v[10:11], v[10:11], v[130:131]
	v_pk_mul_f32 v[12:13], v[12:13], v[132:133]
	v_pk_mul_f32 v[14:15], v[14:15], v[134:135]
	v_pk_mul_f32 v[20:21], v[20:21], v[0:1]
	v_pk_mul_f32 v[22:23], v[22:23], v[2:3]
	v_pk_mul_f32 v[24:25], v[24:25], v[4:5]
	v_pk_mul_f32 v[26:27], v[26:27], v[6:7]
	v_cvt_pk_bf16_f32 v8, v8, v9
	v_cvt_pk_bf16_f32 v9, v10, v11
	v_cvt_pk_bf16_f32 v12, v12, v13
	v_cvt_pk_bf16_f32 v13, v14, v15
	v_cvt_pk_bf16_f32 v20, v20, v21
	v_cvt_pk_bf16_f32 v21, v22, v23
	v_cvt_pk_bf16_f32 v24, v24, v25
	v_cvt_pk_bf16_f32 v25, v26, v27
	global_store_dwordx2 v19, v[8:9], s[8:9] offset:0
	global_store_dwordx2 v19, v[12:13], s[8:9] offset:512
	global_store_dwordx2 v19, v[20:21], s[8:9] offset:1024
	global_store_dwordx2 v19, v[24:25], s[8:9] offset:1536
	s_add_u32 s8, s8, 0x800000
	s_addc_u32 s9, s9, 0
	v_mov_b32_e32 v108, v202
	v_mov_b32_e32 v109, v203
	v_mov_b32_e32 v110, v202
	v_mov_b32_e32 v111, v203
	v_mov_b32_e32 v112, v202
	v_mov_b32_e32 v113, v203
	v_mov_b32_e32 v114, v202
	v_mov_b32_e32 v115, v203
	v_mov_b32_e32 v116, v202
	v_mov_b32_e32 v117, v203
	v_mov_b32_e32 v118, v202
	v_mov_b32_e32 v119, v203
	v_mov_b32_e32 v120, v202
	v_mov_b32_e32 v121, v203
	v_mov_b32_e32 v122, v202
	v_mov_b32_e32 v123, v203
	s_waitcnt vmcnt(40)
	v_pk_fma_f32 v[108:109], v[140:141], v[32:33], v[108:109]
	v_pk_fma_f32 v[108:109], v[142:143], v[34:35], v[108:109]
	v_pk_fma_f32 v[110:111], v[140:141], v[34:35], v[110:111]
	s_waitcnt vmcnt(38)
	v_pk_fma_f32 v[108:109], v[144:145], v[36:37], v[108:109]
	v_pk_fma_f32 v[110:111], v[142:143], v[36:37], v[110:111]
	v_pk_fma_f32 v[112:113], v[140:141], v[36:37], v[112:113]
	v_pk_fma_f32 v[108:109], v[146:147], v[38:39], v[108:109]
	v_pk_fma_f32 v[110:111], v[144:145], v[38:39], v[110:111]
	v_pk_fma_f32 v[112:113], v[142:143], v[38:39], v[112:113]
	v_pk_fma_f32 v[114:115], v[140:141], v[38:39], v[114:115]
	s_waitcnt vmcnt(36)
	v_pk_fma_f32 v[108:109], v[148:149], v[40:41], v[108:109]
	v_pk_fma_f32 v[110:111], v[146:147], v[40:41], v[110:111]
	v_pk_fma_f32 v[112:113], v[144:145], v[40:41], v[112:113]
	v_pk_fma_f32 v[114:115], v[142:143], v[40:41], v[114:115]
	v_pk_fma_f32 v[116:117], v[140:141], v[40:41], v[116:117]
	v_pk_fma_f32 v[108:109], v[150:151], v[42:43], v[108:109]
	v_pk_fma_f32 v[110:111], v[148:149], v[42:43], v[110:111]
	v_pk_fma_f32 v[112:113], v[146:147], v[42:43], v[112:113]
	v_pk_fma_f32 v[114:115], v[144:145], v[42:43], v[114:115]
	v_pk_fma_f32 v[116:117], v[142:143], v[42:43], v[116:117]
	v_pk_fma_f32 v[118:119], v[140:141], v[42:43], v[118:119]
	s_waitcnt vmcnt(34)
	v_pk_fma_f32 v[108:109], v[152:153], v[44:45], v[108:109]
	v_pk_fma_f32 v[110:111], v[150:151], v[44:45], v[110:111]
	v_pk_fma_f32 v[112:113], v[148:149], v[44:45], v[112:113]
	v_pk_fma_f32 v[114:115], v[146:147], v[44:45], v[114:115]
	v_pk_fma_f32 v[116:117], v[144:145], v[44:45], v[116:117]
	v_pk_fma_f32 v[118:119], v[142:143], v[44:45], v[118:119]
	v_pk_fma_f32 v[120:121], v[140:141], v[44:45], v[120:121]
	v_pk_fma_f32 v[108:109], v[154:155], v[46:47], v[108:109]
	v_pk_fma_f32 v[110:111], v[152:153], v[46:47], v[110:111]
	v_pk_fma_f32 v[112:113], v[150:151], v[46:47], v[112:113]
	v_pk_fma_f32 v[114:115], v[148:149], v[46:47], v[114:115]
	v_pk_fma_f32 v[116:117], v[146:147], v[46:47], v[116:117]
	v_pk_fma_f32 v[118:119], v[144:145], v[46:47], v[118:119]
	v_pk_fma_f32 v[120:121], v[142:143], v[46:47], v[120:121]
	v_pk_fma_f32 v[122:123], v[140:141], v[46:47], v[122:123]
	s_waitcnt vmcnt(32)
	v_pk_fma_f32 v[108:109], v[156:157], v[48:49], v[108:109]
	v_pk_fma_f32 v[110:111], v[154:155], v[48:49], v[110:111]
	v_pk_fma_f32 v[112:113], v[152:153], v[48:49], v[112:113]
	v_pk_fma_f32 v[114:115], v[150:151], v[48:49], v[114:115]
	v_pk_fma_f32 v[116:117], v[148:149], v[48:49], v[116:117]
	v_pk_fma_f32 v[118:119], v[146:147], v[48:49], v[118:119]
	v_pk_fma_f32 v[120:121], v[144:145], v[48:49], v[120:121]
	v_pk_fma_f32 v[122:123], v[142:143], v[48:49], v[122:123]
	v_pk_fma_f32 v[108:109], v[158:159], v[50:51], v[108:109]
	v_pk_fma_f32 v[110:111], v[156:157], v[50:51], v[110:111]
	v_pk_fma_f32 v[112:113], v[154:155], v[50:51], v[112:113]
	v_pk_fma_f32 v[114:115], v[152:153], v[50:51], v[114:115]
	v_pk_fma_f32 v[116:117], v[150:151], v[50:51], v[116:117]
	v_pk_fma_f32 v[118:119], v[148:149], v[50:51], v[118:119]
	v_pk_fma_f32 v[120:121], v[146:147], v[50:51], v[120:121]
	v_pk_fma_f32 v[122:123], v[144:145], v[50:51], v[122:123]
	s_waitcnt vmcnt(30)
	v_pk_fma_f32 v[108:109], v[160:161], v[52:53], v[108:109]
	v_pk_fma_f32 v[110:111], v[158:159], v[52:53], v[110:111]
	v_pk_fma_f32 v[112:113], v[156:157], v[52:53], v[112:113]
	v_pk_fma_f32 v[114:115], v[154:155], v[52:53], v[114:115]
	v_pk_fma_f32 v[116:117], v[152:153], v[52:53], v[116:117]
	v_pk_fma_f32 v[118:119], v[150:151], v[52:53], v[118:119]
	v_pk_fma_f32 v[120:121], v[148:149], v[52:53], v[120:121]
	v_pk_fma_f32 v[122:123], v[146:147], v[52:53], v[122:123]
	v_pk_fma_f32 v[108:109], v[162:163], v[54:55], v[108:109]
	v_pk_fma_f32 v[110:111], v[160:161], v[54:55], v[110:111]
	v_pk_fma_f32 v[112:113], v[158:159], v[54:55], v[112:113]
	v_pk_fma_f32 v[114:115], v[156:157], v[54:55], v[114:115]
	v_pk_fma_f32 v[116:117], v[154:155], v[54:55], v[116:117]
	v_pk_fma_f32 v[118:119], v[152:153], v[54:55], v[118:119]
	v_pk_fma_f32 v[120:121], v[150:151], v[54:55], v[120:121]
	v_pk_fma_f32 v[122:123], v[148:149], v[54:55], v[122:123]
	s_waitcnt vmcnt(28)
	v_pk_fma_f32 v[108:109], v[164:165], v[56:57], v[108:109]
	v_pk_fma_f32 v[110:111], v[162:163], v[56:57], v[110:111]
	v_pk_fma_f32 v[112:113], v[160:161], v[56:57], v[112:113]
	v_pk_fma_f32 v[114:115], v[158:159], v[56:57], v[114:115]
	v_pk_fma_f32 v[116:117], v[156:157], v[56:57], v[116:117]
	v_pk_fma_f32 v[118:119], v[154:155], v[56:57], v[118:119]
	v_pk_fma_f32 v[120:121], v[152:153], v[56:57], v[120:121]
	v_pk_fma_f32 v[122:123], v[150:151], v[56:57], v[122:123]
	v_pk_fma_f32 v[108:109], v[166:167], v[58:59], v[108:109]
	v_pk_fma_f32 v[110:111], v[164:165], v[58:59], v[110:111]
	v_pk_fma_f32 v[112:113], v[162:163], v[58:59], v[112:113]
	v_pk_fma_f32 v[114:115], v[160:161], v[58:59], v[114:115]
	v_pk_fma_f32 v[116:117], v[158:159], v[58:59], v[116:117]
	v_pk_fma_f32 v[118:119], v[156:157], v[58:59], v[118:119]
	v_pk_fma_f32 v[120:121], v[154:155], v[58:59], v[120:121]
	v_pk_fma_f32 v[122:123], v[152:153], v[58:59], v[122:123]
	s_waitcnt vmcnt(26)
	v_pk_fma_f32 v[108:109], v[168:169], v[60:61], v[108:109]
	v_pk_fma_f32 v[110:111], v[166:167], v[60:61], v[110:111]
	v_pk_fma_f32 v[112:113], v[164:165], v[60:61], v[112:113]
	v_pk_fma_f32 v[114:115], v[162:163], v[60:61], v[114:115]
	v_pk_fma_f32 v[116:117], v[160:161], v[60:61], v[116:117]
	v_pk_fma_f32 v[118:119], v[158:159], v[60:61], v[118:119]
	v_pk_fma_f32 v[120:121], v[156:157], v[60:61], v[120:121]
	v_pk_fma_f32 v[122:123], v[154:155], v[60:61], v[122:123]
	v_pk_fma_f32 v[108:109], v[170:171], v[62:63], v[108:109]
	v_pk_fma_f32 v[110:111], v[168:169], v[62:63], v[110:111]
	v_pk_fma_f32 v[112:113], v[166:167], v[62:63], v[112:113]
	v_pk_fma_f32 v[114:115], v[164:165], v[62:63], v[114:115]
	v_pk_fma_f32 v[116:117], v[162:163], v[62:63], v[116:117]
	v_pk_fma_f32 v[118:119], v[160:161], v[62:63], v[118:119]
	v_pk_fma_f32 v[120:121], v[158:159], v[62:63], v[120:121]
	v_pk_fma_f32 v[122:123], v[156:157], v[62:63], v[122:123]
	s_waitcnt vmcnt(24)
	v_pk_fma_f32 v[108:109], v[172:173], v[64:65], v[108:109]
	v_pk_fma_f32 v[110:111], v[170:171], v[64:65], v[110:111]
	v_pk_fma_f32 v[112:113], v[168:169], v[64:65], v[112:113]
	v_pk_fma_f32 v[114:115], v[166:167], v[64:65], v[114:115]
	v_pk_fma_f32 v[116:117], v[164:165], v[64:65], v[116:117]
	v_pk_fma_f32 v[118:119], v[162:163], v[64:65], v[118:119]
	v_pk_fma_f32 v[120:121], v[160:161], v[64:65], v[120:121]
	v_pk_fma_f32 v[122:123], v[158:159], v[64:65], v[122:123]
	v_pk_fma_f32 v[108:109], v[174:175], v[66:67], v[108:109]
	v_pk_fma_f32 v[110:111], v[172:173], v[66:67], v[110:111]
	v_pk_fma_f32 v[112:113], v[170:171], v[66:67], v[112:113]
	v_pk_fma_f32 v[114:115], v[168:169], v[66:67], v[114:115]
	v_pk_fma_f32 v[116:117], v[166:167], v[66:67], v[116:117]
	v_pk_fma_f32 v[118:119], v[164:165], v[66:67], v[118:119]
	v_pk_fma_f32 v[120:121], v[162:163], v[66:67], v[120:121]
	v_pk_fma_f32 v[122:123], v[160:161], v[66:67], v[122:123]
	s_waitcnt vmcnt(22)
	v_pk_fma_f32 v[108:109], v[176:177], v[68:69], v[108:109]
	v_pk_fma_f32 v[110:111], v[174:175], v[68:69], v[110:111]
	v_pk_fma_f32 v[112:113], v[172:173], v[68:69], v[112:113]
	v_pk_fma_f32 v[114:115], v[170:171], v[68:69], v[114:115]
	v_pk_fma_f32 v[116:117], v[168:169], v[68:69], v[116:117]
	v_pk_fma_f32 v[118:119], v[166:167], v[68:69], v[118:119]
	v_pk_fma_f32 v[120:121], v[164:165], v[68:69], v[120:121]
	v_pk_fma_f32 v[122:123], v[162:163], v[68:69], v[122:123]
	v_pk_fma_f32 v[108:109], v[178:179], v[70:71], v[108:109]
	v_pk_fma_f32 v[110:111], v[176:177], v[70:71], v[110:111]
	v_pk_fma_f32 v[112:113], v[174:175], v[70:71], v[112:113]
	v_pk_fma_f32 v[114:115], v[172:173], v[70:71], v[114:115]
	v_pk_fma_f32 v[116:117], v[170:171], v[70:71], v[116:117]
	v_pk_fma_f32 v[118:119], v[168:169], v[70:71], v[118:119]
	v_pk_fma_f32 v[120:121], v[166:167], v[70:71], v[120:121]
	v_pk_fma_f32 v[122:123], v[164:165], v[70:71], v[122:123]
	s_waitcnt vmcnt(20)
	v_pk_fma_f32 v[108:109], v[180:181], v[72:73], v[108:109]
	v_pk_fma_f32 v[110:111], v[178:179], v[72:73], v[110:111]
	v_pk_fma_f32 v[112:113], v[176:177], v[72:73], v[112:113]
	v_pk_fma_f32 v[114:115], v[174:175], v[72:73], v[114:115]
	v_pk_fma_f32 v[116:117], v[172:173], v[72:73], v[116:117]
	v_pk_fma_f32 v[118:119], v[170:171], v[72:73], v[118:119]
	v_pk_fma_f32 v[120:121], v[168:169], v[72:73], v[120:121]
	v_pk_fma_f32 v[122:123], v[166:167], v[72:73], v[122:123]
	v_pk_fma_f32 v[108:109], v[182:183], v[74:75], v[108:109]
	v_pk_fma_f32 v[110:111], v[180:181], v[74:75], v[110:111]
	v_pk_fma_f32 v[112:113], v[178:179], v[74:75], v[112:113]
	v_pk_fma_f32 v[114:115], v[176:177], v[74:75], v[114:115]
	v_pk_fma_f32 v[116:117], v[174:175], v[74:75], v[116:117]
	v_pk_fma_f32 v[118:119], v[172:173], v[74:75], v[118:119]
	v_pk_fma_f32 v[120:121], v[170:171], v[74:75], v[120:121]
	v_pk_fma_f32 v[122:123], v[168:169], v[74:75], v[122:123]
	s_waitcnt vmcnt(18)
	v_pk_fma_f32 v[108:109], v[184:185], v[76:77], v[108:109]
	v_pk_fma_f32 v[110:111], v[182:183], v[76:77], v[110:111]
	v_pk_fma_f32 v[112:113], v[180:181], v[76:77], v[112:113]
	v_pk_fma_f32 v[114:115], v[178:179], v[76:77], v[114:115]
	v_pk_fma_f32 v[116:117], v[176:177], v[76:77], v[116:117]
	v_pk_fma_f32 v[118:119], v[174:175], v[76:77], v[118:119]
	v_pk_fma_f32 v[120:121], v[172:173], v[76:77], v[120:121]
	v_pk_fma_f32 v[122:123], v[170:171], v[76:77], v[122:123]
	v_pk_fma_f32 v[108:109], v[186:187], v[78:79], v[108:109]
	v_pk_fma_f32 v[110:111], v[184:185], v[78:79], v[110:111]
	v_pk_fma_f32 v[112:113], v[182:183], v[78:79], v[112:113]
	v_pk_fma_f32 v[114:115], v[180:181], v[78:79], v[114:115]
	v_pk_fma_f32 v[116:117], v[178:179], v[78:79], v[116:117]
	v_pk_fma_f32 v[118:119], v[176:177], v[78:79], v[118:119]
	v_pk_fma_f32 v[120:121], v[174:175], v[78:79], v[120:121]
	v_pk_fma_f32 v[122:123], v[172:173], v[78:79], v[122:123]
	s_waitcnt vmcnt(16)
	v_pk_fma_f32 v[108:109], v[188:189], v[80:81], v[108:109]
	v_pk_fma_f32 v[110:111], v[186:187], v[80:81], v[110:111]
	v_pk_fma_f32 v[112:113], v[184:185], v[80:81], v[112:113]
	v_pk_fma_f32 v[114:115], v[182:183], v[80:81], v[114:115]
	v_pk_fma_f32 v[116:117], v[180:181], v[80:81], v[116:117]
	v_pk_fma_f32 v[118:119], v[178:179], v[80:81], v[118:119]
	v_pk_fma_f32 v[120:121], v[176:177], v[80:81], v[120:121]
	v_pk_fma_f32 v[122:123], v[174:175], v[80:81], v[122:123]
	v_pk_fma_f32 v[108:109], v[190:191], v[82:83], v[108:109]
	v_pk_fma_f32 v[110:111], v[188:189], v[82:83], v[110:111]
	v_pk_fma_f32 v[112:113], v[186:187], v[82:83], v[112:113]
	v_pk_fma_f32 v[114:115], v[184:185], v[82:83], v[114:115]
	v_pk_fma_f32 v[116:117], v[182:183], v[82:83], v[116:117]
	v_pk_fma_f32 v[118:119], v[180:181], v[82:83], v[118:119]
	v_pk_fma_f32 v[120:121], v[178:179], v[82:83], v[120:121]
	v_pk_fma_f32 v[122:123], v[176:177], v[82:83], v[122:123]
	s_waitcnt vmcnt(14)
	v_pk_fma_f32 v[108:109], v[192:193], v[84:85], v[108:109]
	v_pk_fma_f32 v[110:111], v[190:191], v[84:85], v[110:111]
	v_pk_fma_f32 v[112:113], v[188:189], v[84:85], v[112:113]
	v_pk_fma_f32 v[114:115], v[186:187], v[84:85], v[114:115]
	v_pk_fma_f32 v[116:117], v[184:185], v[84:85], v[116:117]
	v_pk_fma_f32 v[118:119], v[182:183], v[84:85], v[118:119]
	v_pk_fma_f32 v[120:121], v[180:181], v[84:85], v[120:121]
	v_pk_fma_f32 v[122:123], v[178:179], v[84:85], v[122:123]
	v_pk_fma_f32 v[108:109], v[194:195], v[86:87], v[108:109]
	v_pk_fma_f32 v[110:111], v[192:193], v[86:87], v[110:111]
	v_pk_fma_f32 v[112:113], v[190:191], v[86:87], v[112:113]
	v_pk_fma_f32 v[114:115], v[188:189], v[86:87], v[114:115]
	v_pk_fma_f32 v[116:117], v[186:187], v[86:87], v[116:117]
	v_pk_fma_f32 v[118:119], v[184:185], v[86:87], v[118:119]
	v_pk_fma_f32 v[120:121], v[182:183], v[86:87], v[120:121]
	v_pk_fma_f32 v[122:123], v[180:181], v[86:87], v[122:123]
	s_waitcnt vmcnt(12)
	v_pk_fma_f32 v[108:109], v[196:197], v[88:89], v[108:109]
	v_pk_fma_f32 v[110:111], v[194:195], v[88:89], v[110:111]
	v_pk_fma_f32 v[112:113], v[192:193], v[88:89], v[112:113]
	v_pk_fma_f32 v[114:115], v[190:191], v[88:89], v[114:115]
	v_pk_fma_f32 v[116:117], v[188:189], v[88:89], v[116:117]
	v_pk_fma_f32 v[118:119], v[186:187], v[88:89], v[118:119]
	v_pk_fma_f32 v[120:121], v[184:185], v[88:89], v[120:121]
	v_pk_fma_f32 v[122:123], v[182:183], v[88:89], v[122:123]
	v_pk_fma_f32 v[108:109], v[198:199], v[90:91], v[108:109]
	v_pk_fma_f32 v[110:111], v[196:197], v[90:91], v[110:111]
	v_pk_fma_f32 v[112:113], v[194:195], v[90:91], v[112:113]
	v_pk_fma_f32 v[114:115], v[192:193], v[90:91], v[114:115]
	v_pk_fma_f32 v[116:117], v[190:191], v[90:91], v[116:117]
	v_pk_fma_f32 v[118:119], v[188:189], v[90:91], v[118:119]
	v_pk_fma_f32 v[120:121], v[186:187], v[90:91], v[120:121]
	v_pk_fma_f32 v[122:123], v[184:185], v[90:91], v[122:123]
	s_waitcnt vmcnt(10)
	v_pk_fma_f32 v[108:109], v[200:201], v[92:93], v[108:109]
	v_pk_fma_f32 v[110:111], v[198:199], v[92:93], v[110:111]
	v_pk_fma_f32 v[112:113], v[196:197], v[92:93], v[112:113]
	v_pk_fma_f32 v[114:115], v[194:195], v[92:93], v[114:115]
	v_pk_fma_f32 v[116:117], v[192:193], v[92:93], v[116:117]
	v_pk_fma_f32 v[118:119], v[190:191], v[92:93], v[118:119]
	v_pk_fma_f32 v[120:121], v[188:189], v[92:93], v[120:121]
	v_pk_fma_f32 v[122:123], v[186:187], v[92:93], v[122:123]
	v_pk_fma_f32 v[110:111], v[200:201], v[94:95], v[110:111]
	v_pk_fma_f32 v[112:113], v[198:199], v[94:95], v[112:113]
	v_pk_fma_f32 v[114:115], v[196:197], v[94:95], v[114:115]
	v_pk_fma_f32 v[116:117], v[194:195], v[94:95], v[116:117]
	v_pk_fma_f32 v[118:119], v[192:193], v[94:95], v[118:119]
	v_pk_fma_f32 v[120:121], v[190:191], v[94:95], v[120:121]
	v_pk_fma_f32 v[122:123], v[188:189], v[94:95], v[122:123]
	s_waitcnt vmcnt(8)
	v_pk_fma_f32 v[112:113], v[200:201], v[96:97], v[112:113]
	v_pk_fma_f32 v[114:115], v[198:199], v[96:97], v[114:115]
	v_pk_fma_f32 v[116:117], v[196:197], v[96:97], v[116:117]
	v_pk_fma_f32 v[118:119], v[194:195], v[96:97], v[118:119]
	v_pk_fma_f32 v[120:121], v[192:193], v[96:97], v[120:121]
	v_pk_fma_f32 v[122:123], v[190:191], v[96:97], v[122:123]
	v_pk_fma_f32 v[114:115], v[200:201], v[98:99], v[114:115]
	v_pk_fma_f32 v[116:117], v[198:199], v[98:99], v[116:117]
	v_pk_fma_f32 v[118:119], v[196:197], v[98:99], v[118:119]
	v_pk_fma_f32 v[120:121], v[194:195], v[98:99], v[120:121]
	v_pk_fma_f32 v[122:123], v[192:193], v[98:99], v[122:123]
	s_waitcnt vmcnt(6)
	v_pk_fma_f32 v[116:117], v[200:201], v[100:101], v[116:117]
	v_pk_fma_f32 v[118:119], v[198:199], v[100:101], v[118:119]
	v_pk_fma_f32 v[120:121], v[196:197], v[100:101], v[120:121]
	v_pk_fma_f32 v[122:123], v[194:195], v[100:101], v[122:123]
	v_pk_fma_f32 v[118:119], v[200:201], v[102:103], v[118:119]
	v_pk_fma_f32 v[120:121], v[198:199], v[102:103], v[120:121]
	v_pk_fma_f32 v[122:123], v[196:197], v[102:103], v[122:123]
	s_waitcnt vmcnt(4)
	v_pk_fma_f32 v[120:121], v[200:201], v[104:105], v[120:121]
	v_pk_fma_f32 v[122:123], v[198:199], v[104:105], v[122:123]
	v_pk_fma_f32 v[122:123], v[200:201], v[106:107], v[122:123]
	ds_write_b64 v16, v[108:109] offset:0
	ds_write_b64 v16, v[110:111] offset:4096
	ds_write_b64 v16, v[112:113] offset:8192
	ds_write_b64 v16, v[114:115] offset:12288
	ds_write_b64 v16, v[116:117] offset:16384
	ds_write_b64 v16, v[118:119] offset:20480
	ds_write_b64 v16, v[120:121] offset:24576
	ds_write_b64 v16, v[122:123] offset:28672
	s_waitcnt lgkmcnt(0)
	s_barrier
	ds_read_b128 v[8:11], v17 offset:0
	ds_read_b128 v[12:15], v17 offset:1024
	ds_read_b128 v[20:23], v17 offset:2048
	ds_read_b128 v[24:27], v17 offset:3072
	s_waitcnt lgkmcnt(0)
	s_barrier
	v_pk_add_f32 v[108:109], v[8:9], v[10:11]
	v_pk_add_f32 v[108:109], v[108:109], v[12:13]
	v_pk_add_f32 v[108:109], v[108:109], v[14:15]
	v_pk_add_f32 v[108:109], v[108:109], v[20:21]
	v_pk_add_f32 v[108:109], v[108:109], v[22:23]
	v_pk_add_f32 v[108:109], v[108:109], v[24:25]
	v_pk_add_f32 v[108:109], v[108:109], v[26:27]
	v_add_f32_e32 v108, v108, v109
	s_nop 1
	v_add_f32_dpp v108, v108, v108 quad_perm:[1,0,3,2] row_mask:0xf bank_mask:0xf bound_ctrl:1
	s_nop 1
	v_add_f32_dpp v108, v108, v108 quad_perm:[2,3,0,1] row_mask:0xf bank_mask:0xf bound_ctrl:1
	s_nop 1
	v_add_f32_dpp v108, v108, v108 row_half_mirror row_mask:0xf bank_mask:0xf bound_ctrl:1
	s_nop 1
	v_add_f32_dpp v108, v108, v108 row_mirror row_mask:0xf bank_mask:0xf bound_ctrl:1
	v_mov_b32_e32 v114, v108
	s_nop 1
	v_permlane16_swap_b32 v108, v114
	s_nop 0
	v_add_f32_e32 v108, v108, v114
	v_mov_b32_e32 v114, v108
	s_nop 1
	v_permlane32_swap_b32 v108, v114
	s_nop 0
	v_add_f32_e32 v108, v108, v114
	v_mul_f32_e32 v110, 0x3a800000, v108
	v_pk_add_f32 v[8:9], v[8:9], v[110:111] op_sel_hi:[1,0] neg_lo:[0,1] neg_hi:[0,1]
	v_pk_add_f32 v[10:11], v[10:11], v[110:111] op_sel_hi:[1,0] neg_lo:[0,1] neg_hi:[0,1]
	v_pk_add_f32 v[12:13], v[12:13], v[110:111] op_sel_hi:[1,0] neg_lo:[0,1] neg_hi:[0,1]
	v_pk_add_f32 v[14:15], v[14:15], v[110:111] op_sel_hi:[1,0] neg_lo:[0,1] neg_hi:[0,1]
	v_pk_add_f32 v[20:21], v[20:21], v[110:111] op_sel_hi:[1,0] neg_lo:[0,1] neg_hi:[0,1]
	v_pk_add_f32 v[22:23], v[22:23], v[110:111] op_sel_hi:[1,0] neg_lo:[0,1] neg_hi:[0,1]
	v_pk_add_f32 v[24:25], v[24:25], v[110:111] op_sel_hi:[1,0] neg_lo:[0,1] neg_hi:[0,1]
	v_pk_add_f32 v[26:27], v[26:27], v[110:111] op_sel_hi:[1,0] neg_lo:[0,1] neg_hi:[0,1]
	v_pk_mul_f32 v[108:109], v[8:9], v[8:9]
	v_pk_fma_f32 v[108:109], v[10:11], v[10:11], v[108:109]
	v_pk_fma_f32 v[108:109], v[12:13], v[12:13], v[108:109]
	v_pk_fma_f32 v[108:109], v[14:15], v[14:15], v[108:109]
	v_pk_fma_f32 v[108:109], v[20:21], v[20:21], v[108:109]
	v_pk_fma_f32 v[108:109], v[22:23], v[22:23], v[108:109]
	v_pk_fma_f32 v[108:109], v[24:25], v[24:25], v[108:109]
	v_pk_fma_f32 v[108:109], v[26:27], v[26:27], v[108:109]
	v_add_f32_e32 v108, v108, v109
	s_nop 1
	v_add_f32_dpp v108, v108, v108 quad_perm:[1,0,3,2] row_mask:0xf bank_mask:0xf bound_ctrl:1
	s_nop 1
	v_add_f32_dpp v108, v108, v108 quad_perm:[2,3,0,1] row_mask:0xf bank_mask:0xf bound_ctrl:1
	s_nop 1
	v_add_f32_dpp v108, v108, v108 row_half_mirror row_mask:0xf bank_mask:0xf bound_ctrl:1
	s_nop 1
	v_add_f32_dpp v108, v108, v108 row_mirror row_mask:0xf bank_mask:0xf bound_ctrl:1
	v_mov_b32_e32 v114, v108
	s_nop 1
	v_permlane16_swap_b32 v108, v114
	s_nop 0
	v_add_f32_e32 v108, v108, v114
	v_mov_b32_e32 v114, v108
	s_nop 1
	v_permlane32_swap_b32 v108, v114
	s_nop 0
	v_add_f32_e32 v108, v108, v114
	v_mul_f32_e32 v112, 0x3a800000, v108
	v_add_f32_e32 v112, 0x3727c5ac, v112
	v_rsq_f32_e32 v112, v112
	s_nop 0
	v_pk_mul_f32 v[116:117], v[204:205], v[112:113] op_sel_hi:[1,0]
	v_pk_fma_f32 v[8:9], v[8:9], v[116:117], v[240:241]
	v_pk_mul_f32 v[116:117], v[206:207], v[112:113] op_sel_hi:[1,0]
	v_pk_fma_f32 v[10:11], v[10:11], v[116:117], v[242:243]
	v_pk_mul_f32 v[116:117], v[208:209], v[112:113] op_sel_hi:[1,0]
	v_pk_fma_f32 v[12:13], v[12:13], v[116:117], v[244:245]
	v_pk_mul_f32 v[116:117], v[210:211], v[112:113] op_sel_hi:[1,0]
	v_pk_fma_f32 v[14:15], v[14:15], v[116:117], v[246:247]
	v_pk_mul_f32 v[116:117], v[212:213], v[112:113] op_sel_hi:[1,0]
	v_pk_fma_f32 v[20:21], v[20:21], v[116:117], v[248:249]
	v_pk_mul_f32 v[116:117], v[214:215], v[112:113] op_sel_hi:[1,0]
	v_pk_fma_f32 v[22:23], v[22:23], v[116:117], v[250:251]
	v_pk_mul_f32 v[116:117], v[216:217], v[112:113] op_sel_hi:[1,0]
	v_pk_fma_f32 v[24:25], v[24:25], v[116:117], v[124:125]
	v_pk_mul_f32 v[116:117], v[218:219], v[112:113] op_sel_hi:[1,0]
	v_pk_fma_f32 v[26:27], v[26:27], v[116:117], v[126:127]
	v_mul_f32_e32 v118, 0xbfb8aa3b, v8
	v_mul_f32_e32 v119, 0xbfb8aa3b, v9
	v_mul_f32_e32 v120, 0xbfb8aa3b, v10
	v_mul_f32_e32 v121, 0xbfb8aa3b, v11
	v_mul_f32_e32 v122, 0xbfb8aa3b, v12
	v_mul_f32_e32 v123, 0xbfb8aa3b, v13
	v_mul_f32_e32 v108, 0xbfb8aa3b, v14
	v_mul_f32_e32 v109, 0xbfb8aa3b, v15
	v_mul_f32_e32 v110, 0xbfb8aa3b, v20
	v_mul_f32_e32 v111, 0xbfb8aa3b, v21
	v_mul_f32_e32 v112, 0xbfb8aa3b, v22
	v_mul_f32_e32 v113, 0xbfb8aa3b, v23
	v_mul_f32_e32 v114, 0xbfb8aa3b, v24
	v_mul_f32_e32 v115, 0xbfb8aa3b, v25
	v_mul_f32_e32 v116, 0xbfb8aa3b, v26
	v_mul_f32_e32 v117, 0xbfb8aa3b, v27
	v_exp_f32_e32 v118, v118
	v_exp_f32_e32 v119, v119
	v_exp_f32_e32 v120, v120
	v_exp_f32_e32 v121, v121
	v_exp_f32_e32 v122, v122
	v_exp_f32_e32 v123, v123
	v_exp_f32_e32 v108, v108
	v_exp_f32_e32 v109, v109
	v_exp_f32_e32 v110, v110
	v_exp_f32_e32 v111, v111
	v_exp_f32_e32 v112, v112
	v_exp_f32_e32 v113, v113
	v_exp_f32_e32 v114, v114
	v_exp_f32_e32 v115, v115
	v_exp_f32_e32 v116, v116
	v_exp_f32_e32 v117, v117
	v_add_f32_e32 v118, 1.0, v118
	v_add_f32_e32 v119, 1.0, v119
	v_add_f32_e32 v120, 1.0, v120
	v_add_f32_e32 v121, 1.0, v121
	v_add_f32_e32 v122, 1.0, v122
	v_add_f32_e32 v123, 1.0, v123
	v_add_f32_e32 v108, 1.0, v108
	v_add_f32_e32 v109, 1.0, v109
	v_add_f32_e32 v110, 1.0, v110
	v_add_f32_e32 v111, 1.0, v111
	v_add_f32_e32 v112, 1.0, v112
	v_add_f32_e32 v113, 1.0, v113
	v_add_f32_e32 v114, 1.0, v114
	v_add_f32_e32 v115, 1.0, v115
	v_add_f32_e32 v116, 1.0, v116
	v_add_f32_e32 v117, 1.0, v117
	v_rcp_f32_e32 v118, v118
	v_rcp_f32_e32 v119, v119
	v_rcp_f32_e32 v120, v120
	v_rcp_f32_e32 v121, v121
	v_rcp_f32_e32 v122, v122
	v_rcp_f32_e32 v123, v123
	v_rcp_f32_e32 v108, v108
	v_rcp_f32_e32 v109, v109
	v_rcp_f32_e32 v110, v110
	v_rcp_f32_e32 v111, v111
	v_rcp_f32_e32 v112, v112
	v_rcp_f32_e32 v113, v113
	v_rcp_f32_e32 v114, v114
	v_rcp_f32_e32 v115, v115
	v_rcp_f32_e32 v116, v116
	v_rcp_f32_e32 v117, v117
	v_mul_f32_e32 v8, v8, v118
	v_mul_f32_e32 v9, v9, v119
	v_mul_f32_e32 v10, v10, v120
	v_mul_f32_e32 v11, v11, v121
	v_mul_f32_e32 v12, v12, v122
	v_mul_f32_e32 v13, v13, v123
	v_mul_f32_e32 v14, v14, v108
	v_mul_f32_e32 v15, v15, v109
	v_mul_f32_e32 v20, v20, v110
	v_mul_f32_e32 v21, v21, v111
	v_mul_f32_e32 v22, v22, v112
	v_mul_f32_e32 v23, v23, v113
	v_mul_f32_e32 v24, v24, v114
	v_mul_f32_e32 v25, v25, v115
	v_mul_f32_e32 v26, v26, v116
	v_mul_f32_e32 v27, v27, v117
	v_pk_mul_f32 v[8:9], v[8:9], v[128:129]
	v_pk_mul_f32 v[10:11], v[10:11], v[130:131]
	v_pk_mul_f32 v[12:13], v[12:13], v[132:133]
	v_pk_mul_f32 v[14:15], v[14:15], v[134:135]
	v_pk_mul_f32 v[20:21], v[20:21], v[0:1]
	v_pk_mul_f32 v[22:23], v[22:23], v[2:3]
	v_pk_mul_f32 v[24:25], v[24:25], v[4:5]
	v_pk_mul_f32 v[26:27], v[26:27], v[6:7]
	v_cvt_pk_bf16_f32 v8, v8, v9
	v_cvt_pk_bf16_f32 v9, v10, v11
	v_cvt_pk_bf16_f32 v12, v12, v13
	v_cvt_pk_bf16_f32 v13, v14, v15
	v_cvt_pk_bf16_f32 v20, v20, v21
	v_cvt_pk_bf16_f32 v21, v22, v23
	v_cvt_pk_bf16_f32 v24, v24, v25
	v_cvt_pk_bf16_f32 v25, v26, v27
	global_store_dwordx2 v19, v[8:9], s[8:9] offset:0
	global_store_dwordx2 v19, v[12:13], s[8:9] offset:512
	global_store_dwordx2 v19, v[20:21], s[8:9] offset:1024
	global_store_dwordx2 v19, v[24:25], s[8:9] offset:1536
	s_add_u32 s8, s8, 0x800000
	s_addc_u32 s9, s9, 0
	s_waitcnt vmcnt(0)
	v_lshrrev_b32_e32 v1, 3, v136
	v_lshl_or_b32 v1, v230, 3, v1
	v_and_b32_e32 v2, 7, v231
	v_mov_b32_e32 v67, 0
	v_lshlrev_b32_e32 v66, 8, v1
	v_cmp_eq_u32_e64 s[6:7], 0, v2
	v_lshlrev_b32_e32 v2, 5, v2
	v_lshl_add_u64 v[10:11], s[72:73], 0, v[66:67]
	v_mov_b32_e32 v3, v67
	v_lshl_add_u64 v[68:69], v[10:11], 0, v[2:3]
	v_lshl_add_u64 v[10:11], s[40:41], 0, v[66:67]
	v_add_u32_e32 v137, 0, v2
	v_lshl_add_u64 v[2:3], v[10:11], 0, v[2:3]
	s_mov_b64 s[8:9], 0x6329200
	v_lshlrev_b32_e32 v66, 3, v231
	v_lshl_add_u64 v[70:71], v[2:3], 0, s[8:9]
	v_lshl_add_u64 v[72:73], s[22:23], 0, v[66:67]
	s_mov_b64 s[8:9], 0x1000
	v_lshl_add_u64 v[74:75], v[72:73], 0, s[8:9]
	s_mov_b64 s[8:9], 0x2000
	v_lshl_add_u64 v[76:77], v[72:73], 0, s[8:9]
	s_mov_b64 s[8:9], 0x3000
	v_lshl_add_u64 v[78:79], v[72:73], 0, s[8:9]
	s_mov_b64 s[8:9], 0x4000
	v_lshl_add_u64 v[80:81], v[72:73], 0, s[8:9]
	s_mov_b64 s[8:9], 0x5000
	v_lshl_add_u64 v[82:83], v[72:73], 0, s[8:9]
	s_mov_b64 s[8:9], 0x6000
	v_lshl_add_u64 v[84:85], v[72:73], 0, s[8:9]
	s_mov_b64 s[8:9], 0x7000
	v_lshl_add_u64 v[86:87], v[72:73], 0, s[8:9]
	s_mov_b64 s[8:9], 0x8000
	v_lshl_add_u64 v[88:89], v[72:73], 0, s[8:9]
	s_mov_b64 s[8:9], 0x9000
	v_lshl_add_u64 v[90:91], v[72:73], 0, s[8:9]
	s_mov_b64 s[8:9], 0xa000
	v_lshl_add_u64 v[92:93], v[72:73], 0, s[8:9]
	s_mov_b64 s[8:9], 0xb000
	v_lshl_add_u64 v[94:95], v[72:73], 0, s[8:9]
	s_mov_b64 s[8:9], 0xc000
	v_lshl_add_u64 v[96:97], v[72:73], 0, s[8:9]
	s_mov_b64 s[8:9], 0xd000
	v_lshl_add_u64 v[98:99], v[72:73], 0, s[8:9]
	s_mov_b64 s[8:9], 0xe000
	v_lshl_add_u64 v[100:101], v[72:73], 0, s[8:9]
	s_mov_b64 s[8:9], 0xf000
	v_lshl_add_u64 v[102:103], v[72:73], 0, s[8:9]
	s_mov_b64 s[8:9], 0x10000
	v_lshl_add_u64 v[104:105], v[72:73], 0, s[8:9]
	s_mov_b64 s[8:9], 0x11000
	v_lshl_add_u64 v[106:107], v[72:73], 0, s[8:9]
	s_mov_b64 s[8:9], 0x12000
	v_lshl_add_u64 v[108:109], v[72:73], 0, s[8:9]
	s_mov_b64 s[8:9], 0x13000
	v_lshl_add_u64 v[110:111], v[72:73], 0, s[8:9]
	s_mov_b64 s[8:9], 0x14000
	v_lshl_add_u64 v[112:113], v[72:73], 0, s[8:9]
	s_mov_b64 s[8:9], 0x15000
	v_lshl_add_u64 v[114:115], v[72:73], 0, s[8:9]
	s_mov_b64 s[8:9], 0x16000
	v_lshl_add_u64 v[116:117], v[72:73], 0, s[8:9]
	s_mov_b64 s[8:9], 0x17000
	v_lshl_add_u64 v[118:119], v[72:73], 0, s[8:9]
	s_mov_b64 s[8:9], 0x18000
	s_add_u32 s68, s42, 0x1d300000
	v_lshl_add_u64 v[120:121], v[72:73], 0, s[8:9]
	s_mov_b64 s[8:9], 0x19000
	s_addc_u32 s69, s43, 0
	v_lshl_add_u64 v[122:123], v[72:73], 0, s[8:9]
	s_mov_b64 s[8:9], 0x1a000
	s_add_u32 s40, s42, 0x1f380800
	v_lshl_add_u64 v[124:125], v[72:73], 0, s[8:9]
	s_mov_b64 s[8:9], 0x1b000
	s_addc_u32 s41, s43, 0
	v_lshl_add_u64 v[126:127], v[72:73], 0, s[8:9]
	s_mov_b64 s[8:9], 0x1c000
	v_lshlrev_b32_e32 v0, 4, v136
	v_lshl_add_u32 v240, v1, 2, 0
	v_lshl_add_u64 v[128:129], v[72:73], 0, s[8:9]
	s_mov_b64 s[8:9], 0x1d000
	s_add_u32 s22, s42, 0x29700000
	v_mov_b32_e32 v1, v67
	v_add_u32_e32 v5, 0, v0
	v_lshlrev_b32_e32 v7, 12, v230
	v_or_b32_e32 v4, 64, v136
	v_or_b32_e32 v6, 0x80, v136
	v_or_b32_e32 v8, 0xc0, v136
	v_lshl_add_u64 v[130:131], v[72:73], 0, s[8:9]
	s_mov_b64 s[8:9], 0x1e000
	s_addc_u32 s23, s43, 0
	v_lshl_add_u64 v[134:135], s[24:25], 0, v[66:67]
	v_lshl_add_u64 v[142:143], s[26:27], 0, v[0:1]
	v_lshl_add_u64 v[144:145], s[36:37], 0, v[0:1]
	v_lshl_add_u64 v[146:147], s[70:71], 0, v[0:1]
	s_lshl_b32 s3, s2, 15
	v_mov_b32_e32 v0, 0xfff70000
	s_mov_b32 s24, 0xf9700000
	s_mov_b32 s67, 0
	v_add_u32_e32 v65, 0, v138
	v_lshlrev_b32_e32 v64, 1, v231
	v_lshl_add_u64 v[132:133], v[72:73], 0, s[8:9]
	v_lshl_add_u64 v[140:141], s[22:23], 0, v[66:67]
	s_add_i32 s66, s3, 0xfdc00000
	s_lshl_b32 s3, s34, 15
	v_lshl_add_u32 v241, v18, 6, v0
	s_lshl_b32 s83, s34, 9
	s_sub_i32 s84, s74, 30
	s_lshl_b32 s85, s34, 3
	s_movk_i32 s86, 0x2000
	s_movk_i32 s87, 0x3c0
	s_movk_i32 s88, 0xd20
	s_mov_b32 s25, -1
	s_mov_b32 s89, 0xf800000
	v_mov_b32_e32 v242, 0x260
	v_mov_b32_e32 v243, 0x3a27c5ac
	v_add_u32_e32 v244, v5, v7
	v_mov_b32_e32 v245, 0x3727c5ac
	s_mov_b64 s[26:27], 0x2bf00800
	s_mov_b32 s90, 0xbfb8aa3b
	s_mov_b32 s91, 0x42ce8ed0
	s_mov_b32 s92, 0xc2b17218
	v_lshlrev_b32_e32 v148, 3, v4
	v_lshlrev_b32_e32 v150, 3, v6
	v_lshlrev_b32_e32 v152, 3, v8
	v_mov_b32_e32 v246, 0x7f800000
	s_mov_b32 s93, s2
	s_lshl_b32 s75, s34, 2
	s_add_i32 s93, s93, s75
	s_lshl_b32 s75, s3, 2
	s_add_i32 s66, s66, s75
	s_lshl_b32 s75, s85, 2
	s_add_i32 s84, s84, s75
	s_lshl_b32 s75, s83, 2
	v_add_u32_e32 v241, s75, v241
	s_branch .LBB0_1309
